# ACT tile re-layout plus chunk-state (S_prev) block re-layout: h1 stores and H3 loads become contiguous 1 KiB per wave access, scan decay index remapped
# speedup vs baseline: 1.0063x; 1.0041x over previous
; __device__ __forceinline__ unsigned cvt_pk_bf16_c(float lo, float hi) { const f32x2_t v = {lo, hi}; return __builtin_bit_cast(unsigned, __builtin_convertvector(v, bf16x2_t)); }
;     __host__ __device__ __forceinline__ int item(int k) const { const int vv = vid + (k >> 3) * G; if (vv >= 256) return -1; const int pm = vv >> 2, p = vv & 3, j = k & 7; return (((pm >> 4) * 8 + 2 * p + (j >> 2)) << 6) + (pm & 15) * 4 + (j & 3); }
; #define LAS __attribute__((address_space(3)))
; template <class Ord> __device__ __forceinline__ void hgrn_h1(LAS unsigned char* lds, const _Float16* LF, const bf16_t* V, bf16_t* DS, float* DEC, const Ord& O, int tid) {
;     const int w = __builtin_amdgcn_readfirstlane(tid >> 6), lane0 = tid & 63, grp = w >> 2, wl = w & 3;
;     LAS unsigned char* gb = lds + grp * 50176;
;     LAS float* LS = (LAS float*)gb; LAS unsigned char* vl = gb + 33792;
;     ...
;             bf16_t* dsp = DS + (size_t)item * (HD * HD);
; #pragma unroll
;             for (int c = 0; c < 8; ++c) { f32x4 acc0 = (f32x4){0.f, 0.f, 0.f, 0.f}, acc1 = (f32x4){0.f, 0.f, 0.f, 0.f};
; #pragma unroll
;                 for (int ks = 0; ks < 2; ++ks) { const s16x4 lo = vl_tr_read(vl, 32 * ks + 8 * fq, c, lane), hi = vl_tr_read(vl, 32 * ks + 8 * fq + 4, c, lane);
;                     const bf16x8 vf = __builtin_shufflevector(lo, hi, 0, 1, 2, 3, 4, 5, 6, 7);
;                     acc0 = __builtin_amdgcn_mfma_f32_16x16x32_bf16(kf[0][ks], vf, acc0, 0, 0, 0);
;                     acc1 = __builtin_amdgcn_mfma_f32_16x16x32_bf16(kf[1][ks], vf, acc1, 0, 0, 0); }
;                 u32x2 o0, o1; o0.x = cvt_pk_bf16_c(acc0.x, acc0.y); o0.y = cvt_pk_bf16_c(acc0.z, acc0.w); o1.x = cvt_pk_bf16_c(acc1.x, acc1.y); o1.y = cvt_pk_bf16_c(acc1.z, acc1.w);
;                 const auto r0 = __builtin_amdgcn_permlane16_swap(o0.x, o1.x, false, false); const auto r1 = __builtin_amdgcn_permlane16_swap(o0.y, o1.y, false, false);
;                 u32x4 wv; wv.x = r0[0]; wv.y = r1[0]; wv.z = r0[1]; wv.w = r1[1];
;                 store_wt(dsp + (size_t)(16 * c + fr) * HD + 32 * wl + ((fq & 1) ? 16 + 4 * (fq - 1) : 4 * fq), wv); }
;             if (fq == 0) { __hip_atomic_store(&DEC[(size_t)item * HD + 32 * wl + fr], __expf(bl[0]), __ATOMIC_RELAXED, __HIP_MEMORY_SCOPE_AGENT); __hip_atomic_store(&DEC[(size_t)item * HD + 32 * wl + 16 + fr], __expf(bl[1]), __ATOMIC_RELAXED, __HIP_MEMORY_SCOPE_AGENT); }
.LBB0_636:
	s_bitcmp1_b32 s85, 28
	s_cselect_b64 s[8:9], -1, 0
	s_xor_b64 s[14:15], s[30:31], -1
	s_or_b64 s[8:9], s[14:15], s[8:9]
	s_and_b64 vcc, exec, s[8:9]
	s_cbranch_vccnz .LBB0_649
	s_mul_i32 s7, s2, 0xc400
	s_add_i32 s8, s7, 0
	s_lshl_b32 s9, s6, 6
	s_lshl_b32 s6, s6, 7
	s_add_i32 s14, s8, s6
	s_add_u32 s7, s67, s9
	s_addc_u32 s16, s33, 0
	s_add_u32 s15, s7, 0x44a04000
	s_addc_u32 s16, s16, 0
	s_mul_i32 s7, s9, 15
	s_add_u32 s15, s15, s7
	s_addc_u32 s16, s16, 0
	s_add_u32 s6, s67, s6
	s_addc_u32 s7, s33, 0
	s_add_u32 s17, s6, 0x48a04000
	s_addc_u32 s18, s7, 0
	s_mov_b32 s19, 2
	s_branch .LBB0_640

; __device__ __forceinline__ float bperm(float v, int src_lane) { return __int_as_float(__builtin_amdgcn_ds_bpermute(src_lane << 2, __float_as_int(v))); }
; __device__ __forceinline__ bf16x8 pack8f(const float (&v)[8]) { u32x4 pk; pk.x = cvt_pk_bf16_c(v[0], v[1]); pk.y = cvt_pk_bf16_c(v[2], v[3]); pk.z = cvt_pk_bf16_c(v[4], v[5]); pk.w = cvt_pk_bf16_c(v[6], v[7]); return __builtin_bit_cast(bf16x8, pk); }
; __device__ __forceinline__ void cumsum_from(const float (&lf)[2][8], int fr, int fq, float (&b)[2][8], float& blast) {
; #pragma unroll
;     for (int ks = 0; ks < 2; ++ks) { b[ks][0] = lf[ks][0];
; #pragma unroll
;         for (int i = 1; i < 8; ++i) b[ks][i] = b[ks][i - 1] + lf[ks][i]; }
;     const float T0 = b[0][7], T1 = b[1][7]; float x0 = T0, x1 = T1, y;
;     const int ln = fr + 16 * fq;
;     y = bperm(x0, (ln - 16) & 63); if (fq >= 1) x0 += y;
;     y = bperm(x0, (ln - 32) & 63); if (fq >= 2) x0 += y;
;     y = bperm(x1, (ln - 16) & 63); if (fq >= 1) x1 += y;
;     y = bperm(x1, (ln - 32) & 63); if (fq >= 2) x1 += y;
;     const float tot0 = bperm(x0, fr + 48), tot1 = bperm(x1, fr + 48);
;     const float off0 = x0 - T0, off1 = tot0 + x1 - T1;
; #pragma unroll
;     for (int i = 0; i < 8; ++i) { b[0][i] += off0; b[1][i] += off1; }
;     blast = tot0 + tot1;
; }
; template <class Ord> __device__ __forceinline__ void hgrn_h1(LAS unsigned char* lds, const _Float16* LF, const bf16_t* V, bf16_t* DS, float* DEC, const Ord& O, int tid) {
;     ...
;             for (int ps = 0; ps < 2; ++ps) { float lf[2][8], b[2][8]; const int d = 16 * (2 * wl + ps) + fr;
; #pragma unroll
;                 for (int ks = 0; ks < 2; ++ks)
; #pragma unroll
;                     for (int i = 0; i < 8; ++i) lf[ks][i] = LS[(32 * ks + 8 * fq + i) * 132 + d];
;                 cumsum_from(lf, fr, fq, b, bl[ps]);
; #pragma unroll
;                 for (int ks = 0; ks < 2; ++ks) { float kv[8];
; #pragma unroll
;                     for (int i = 0; i < 8; ++i) kv[i] = (1.f - __expf(lf[ks][i])) * __expf(bl[ps] - b[ks][i]);
;                     kf[ps][ks] = pack8f(kv); } }
.LBB0_646:
	s_andn2_b64 vcc, exec, s[6:7]
	s_cbranch_vccnz .LBB0_639
	v_ashrrev_i32_e32 v0, 4, v79
	v_lshlrev_b32_e32 v80, 2, v81
	v_lshl_or_b32 v35, v0, 6, v80
	v_add_u32_e32 v34, s14, v80
	v_add_u32_e32 v36, 0xc0, v35
	v_and_b32_e32 v83, 0xfc, v36
	v_mad_u64_u32 v[36:37], s[6:7], v0, s92, v[34:35]
	v_bitop3_b32 v90, v35, s84, v243 bitop3:0x6c
	v_add_u32_e32 v35, 0x400, v36
	v_lshlrev_b32_e32 v82, 3, v0
	ds_read2_b32 v[76:77], v36 offset1:16
	ds_read2_b32 v[74:75], v36 offset0:132 offset1:148
	ds_read2_b32 v[72:73], v35 offset0:8 offset1:24
	ds_read2_b32 v[70:71], v35 offset0:140 offset1:156
	v_add_u32_e32 v35, 0x800, v36
	ds_read2_b32 v[68:69], v35 offset0:16 offset1:32
	ds_read2_b32 v[66:67], v35 offset0:148 offset1:164
	v_add_u32_e32 v35, 0xc00, v36
	v_add_u32_e32 v91, 32, v82
	ds_read2_b32 v[44:45], v35 offset0:24 offset1:40
	ds_read2_b32 v[42:43], v35 offset0:156 offset1:172
	v_mad_u64_u32 v[34:35], s[6:7], v91, s62, v[34:35]
	ds_read2_b32 v[64:65], v34 offset1:16
	v_add_u32_e32 v34, 0x4400, v36
	ds_read2_b32 v[62:63], v34 offset0:4 offset1:20
	ds_read2_b32 v[60:61], v34 offset0:136 offset1:152
	v_add_u32_e32 v34, 0x4800, v36
	ds_read2_b32 v[58:59], v34 offset0:12 offset1:28
	ds_read2_b32 v[56:57], v34 offset0:144 offset1:160
	v_add_u32_e32 v34, 0x4c00, v36
	ds_read2_b32 v[54:55], v34 offset0:20 offset1:36
	ds_read2_b32 v[48:49], v34 offset0:152 offset1:168
	v_add_u32_e32 v34, 0x5000, v36
	s_waitcnt lgkmcnt(13)
	v_add_f32_e32 v36, v76, v74
	s_waitcnt lgkmcnt(12)
	v_add_f32_e32 v38, v36, v72
	s_waitcnt lgkmcnt(11)
	v_add_f32_e32 v39, v38, v70
	s_waitcnt lgkmcnt(5)
	v_add_f32_e32 v52, v64, v62
	ds_read2_b32 v[46:47], v34 offset0:28 offset1:44
	v_add_f32_e32 v40, v39, v68
	s_waitcnt lgkmcnt(5)
	v_add_f32_e32 v53, v52, v60
	v_add_f32_e32 v41, v40, v66
	s_waitcnt lgkmcnt(4)
	v_add_f32_e32 v84, v53, v58
	v_add_f32_e32 v50, v41, v44
	s_waitcnt lgkmcnt(3)
	v_add_f32_e32 v85, v84, v56
	v_add_f32_e32 v51, v50, v42
	s_waitcnt lgkmcnt(2)
	v_add_f32_e32 v86, v85, v54
	ds_bpermute_b32 v34, v83, v51
	s_waitcnt lgkmcnt(2)
	v_add_f32_e32 v87, v86, v48
	s_waitcnt lgkmcnt(1)
	v_add_f32_e32 v35, v87, v46
	ds_bpermute_b32 v88, v83, v35
	v_cmp_lt_i32_e32 vcc, 0, v0
	s_waitcnt lgkmcnt(1)
	v_add_f32_e32 v34, v51, v34
	v_cmp_lt_i32_e64 s[6:7], 1, v0
	v_cndmask_b32_e32 v34, v51, v34, vcc
	ds_bpermute_b32 v37, v90, v34
	s_waitcnt lgkmcnt(1)
	v_add_f32_e32 v88, v35, v88
	v_cndmask_b32_e32 v88, v35, v88, vcc
	ds_bpermute_b32 v89, v90, v88
	v_mul_f32_e32 v44, 0x3fb8aa3b, v44
	s_waitcnt lgkmcnt(1)
	v_add_f32_e32 v37, v34, v37
	v_cndmask_b32_e64 v37, v34, v37, s[6:7]
	ds_bpermute_b32 v34, v80, v37 offset:192
	s_waitcnt lgkmcnt(1)
	v_add_f32_e32 v89, v88, v89
	v_cndmask_b32_e64 v88, v88, v89, s[6:7]
	v_sub_f32_e32 v89, v37, v51
	v_add_f32_e32 v94, v36, v89
	ds_bpermute_b32 v36, v80, v88 offset:192
	s_waitcnt lgkmcnt(1)
	v_add_f32_e32 v37, v88, v34
	v_sub_f32_e32 v37, v37, v35
	v_add_f32_e32 v92, v76, v89
	v_add_f32_e32 v95, v52, v37
	v_add_f32_e32 v52, v38, v89
	v_add_f32_e32 v96, v53, v37
	v_add_f32_e32 v53, v39, v89
	v_add_f32_e32 v97, v84, v37
	v_add_f32_e32 v84, v40, v89
	v_add_f32_e32 v98, v85, v37
	v_add_f32_e32 v85, v41, v89
	v_add_f32_e32 v88, v50, v89
	v_add_f32_e32 v89, v51, v89
	s_waitcnt lgkmcnt(0)
	v_pk_add_f32 v[50:51], v[34:35], v[36:37]
	v_add_f32_e32 v93, v64, v37
	v_sub_f32_e32 v35, v50, v92
	v_mul_f32_e32 v35, 0x3fb8aa3b, v35
	v_sub_f32_e32 v39, v50, v52
	v_add_f32_e32 v86, v86, v37
	v_add_f32_e32 v87, v87, v37
	v_mul_f32_e32 v34, 0x3fb8aa3b, v76
	v_exp_f32_e32 v36, v35
	v_mul_f32_e32 v35, 0x3fb8aa3b, v74
	v_sub_f32_e32 v37, v50, v94
	v_mul_f32_e32 v39, 0x3fb8aa3b, v39
	v_exp_f32_e32 v34, v34
	v_exp_f32_e32 v35, v35
	v_mul_f32_e32 v37, 0x3fb8aa3b, v37
	v_mul_f32_e32 v38, 0x3fb8aa3b, v72
	v_exp_f32_e32 v40, v39
	v_mul_f32_e32 v39, 0x3fb8aa3b, v70
	v_exp_f32_e32 v37, v37
	v_exp_f32_e32 v38, v38
	v_exp_f32_e32 v39, v39
	v_sub_f32_e32 v41, v50, v53
	v_mul_f32_e32 v41, 0x3fb8aa3b, v41
	v_exp_f32_e32 v41, v41
	v_pk_add_f32 v[34:35], v[34:35], 1.0 op_sel_hi:[1,0] neg_lo:[1,0] neg_hi:[1,0]
	v_mul_f32_e32 v42, 0x3fb8aa3b, v42
	v_pk_mul_f32 v[34:35], v[34:35], v[36:37]
	v_pk_add_f32 v[36:37], v[38:39], 1.0 op_sel_hi:[1,0] neg_lo:[1,0] neg_hi:[1,0]
	v_sub_f32_e32 v39, v50, v84
	v_mul_f32_e32 v39, 0x3fb8aa3b, v39
	v_pk_mul_f32 v[36:37], v[36:37], v[40:41]
	v_mul_f32_e32 v38, 0x3fb8aa3b, v68
	v_exp_f32_e32 v40, v39
	v_mul_f32_e32 v39, 0x3fb8aa3b, v66
	v_sub_f32_e32 v41, v50, v85
	v_exp_f32_e32 v38, v38
	v_exp_f32_e32 v39, v39
	v_mul_f32_e32 v41, 0x3fb8aa3b, v41
	v_exp_f32_e32 v41, v41
	v_exp_f32_e32 v52, v44
	v_sub_f32_e32 v44, v50, v88
	v_exp_f32_e32 v53, v42
	v_sub_f32_e32 v42, v50, v89
	v_mul_f32_e32 v44, 0x3fb8aa3b, v44
	v_mul_f32_e32 v42, 0x3fb8aa3b, v42
	v_exp_f32_e32 v84, v44
	v_exp_f32_e32 v85, v42
	v_pk_add_f32 v[38:39], v[38:39], 1.0 op_sel_hi:[1,0] neg_lo:[1,0] neg_hi:[1,0]
	v_cvt_pk_bf16_f32 v34, v34, v35
	v_pk_mul_f32 v[38:39], v[38:39], v[40:41]
	v_pk_add_f32 v[40:41], v[52:53], 1.0 op_sel_hi:[1,0] neg_lo:[1,0] neg_hi:[1,0]
	v_cvt_pk_bf16_f32 v35, v36, v37
	v_cvt_pk_bf16_f32 v36, v38, v39
	v_sub_f32_e32 v39, v50, v93
	v_mul_f32_e32 v42, 0x3fb8aa3b, v60
	v_pk_mul_f32 v[40:41], v[40:41], v[84:85]
	v_mul_f32_e32 v39, 0x3fb8aa3b, v39
	v_exp_f32_e32 v52, v42
	v_sub_f32_e32 v42, v50, v96
	v_cvt_pk_bf16_f32 v37, v40, v41
	v_mul_f32_e32 v38, 0x3fb8aa3b, v64
	v_exp_f32_e32 v40, v39
	v_mul_f32_e32 v39, 0x3fb8aa3b, v62
	v_sub_f32_e32 v41, v50, v95
	v_mul_f32_e32 v42, 0x3fb8aa3b, v42
	v_exp_f32_e32 v38, v38
	v_exp_f32_e32 v39, v39
	v_mul_f32_e32 v41, 0x3fb8aa3b, v41
	v_exp_f32_e32 v84, v42
	v_mul_f32_e32 v42, 0x3fb8aa3b, v58
	v_exp_f32_e32 v41, v41
; __device__ __forceinline__ float bperm(float v, int src_lane) { return __int_as_float(__builtin_amdgcn_ds_bpermute(src_lane << 2, __float_as_int(v))); }
; __device__ __forceinline__ bf16x8 pack8f(const float (&v)[8]) { u32x4 pk; pk.x = cvt_pk_bf16_c(v[0], v[1]); pk.y = cvt_pk_bf16_c(v[2], v[3]); pk.z = cvt_pk_bf16_c(v[4], v[5]); pk.w = cvt_pk_bf16_c(v[6], v[7]); return __builtin_bit_cast(bf16x8, pk); }
; __device__ __forceinline__ void cumsum_from(const float (&lf)[2][8], int fr, int fq, float (&b)[2][8], float& blast) {
; #pragma unroll
;     for (int ks = 0; ks < 2; ++ks) { b[ks][0] = lf[ks][0];
; #pragma unroll
;         for (int i = 1; i < 8; ++i) b[ks][i] = b[ks][i - 1] + lf[ks][i]; }
;     const float T0 = b[0][7], T1 = b[1][7]; float x0 = T0, x1 = T1, y;
;     const int ln = fr + 16 * fq;
;     y = bperm(x0, (ln - 16) & 63); if (fq >= 1) x0 += y;
;     y = bperm(x0, (ln - 32) & 63); if (fq >= 2) x0 += y;
;     y = bperm(x1, (ln - 16) & 63); if (fq >= 1) x1 += y;
;     y = bperm(x1, (ln - 32) & 63); if (fq >= 2) x1 += y;
;     const float tot0 = bperm(x0, fr + 48), tot1 = bperm(x1, fr + 48);
;     const float off0 = x0 - T0, off1 = tot0 + x1 - T1;
; #pragma unroll
;     for (int i = 0; i < 8; ++i) { b[0][i] += off0; b[1][i] += off1; }
;     blast = tot0 + tot1;
; }
; template <class Ord> __device__ __forceinline__ void hgrn_h1(LAS unsigned char* lds, const _Float16* LF, const bf16_t* V, bf16_t* DS, float* DEC, const Ord& O, int tid) {
;     ...
;             for (int ps = 0; ps < 2; ++ps) { float lf[2][8], b[2][8]; const int d = 16 * (2 * wl + ps) + fr;
; #pragma unroll
;                 for (int ks = 0; ks < 2; ++ks)
; #pragma unroll
;                     for (int i = 0; i < 8; ++i) lf[ks][i] = LS[(32 * ks + 8 * fq + i) * 132 + d];
;                 cumsum_from(lf, fr, fq, b, bl[ps]);
; #pragma unroll
;                 for (int ks = 0; ks < 2; ++ks) { float kv[8];
; #pragma unroll
;                     for (int i = 0; i < 8; ++i) kv[i] = (1.f - __expf(lf[ks][i])) * __expf(bl[ps] - b[ks][i]);
;                     kf[ps][ks] = pack8f(kv); } }
	v_exp_f32_e32 v53, v42
	v_sub_f32_e32 v42, v50, v97
	v_mul_f32_e32 v42, 0x3fb8aa3b, v42
	v_exp_f32_e32 v85, v42
	v_pk_add_f32 v[38:39], v[38:39], 1.0 op_sel_hi:[1,0] neg_lo:[1,0] neg_hi:[1,0]
	v_mul_f32_e32 v42, 0x3fb8aa3b, v56
	v_pk_mul_f32 v[38:39], v[38:39], v[40:41]
	v_pk_add_f32 v[40:41], v[52:53], 1.0 op_sel_hi:[1,0] neg_lo:[1,0] neg_hi:[1,0]
	v_exp_f32_e32 v52, v42
	v_sub_f32_e32 v42, v50, v98
	v_mul_f32_e32 v42, 0x3fb8aa3b, v42
	v_pk_mul_f32 v[40:41], v[40:41], v[84:85]
	v_exp_f32_e32 v84, v42
	v_mul_f32_e32 v42, 0x3fb8aa3b, v54
	v_exp_f32_e32 v53, v42
	v_sub_f32_e32 v42, v50, v86
	v_mul_f32_e32 v42, 0x3fb8aa3b, v42
	v_exp_f32_e32 v85, v42
	v_mul_f32_e32 v42, 0x3fb8aa3b, v48
	v_exp_f32_e32 v86, v42
	v_sub_f32_e32 v42, v50, v87
	v_mul_f32_e32 v42, 0x3fb8aa3b, v42
	v_exp_f32_e32 v88, v42
	v_mul_f32_e32 v42, 0x3fb8aa3b, v46
	v_exp_f32_e32 v87, v42
	v_sub_f32_e32 v42, v50, v51
	v_mul_f32_e32 v42, 0x3fb8aa3b, v42
	v_exp_f32_e32 v89, v42
	v_add_f32_e32 v42, v77, v75
	v_add_f32_e32 v44, v42, v73
	v_add_f32_e32 v46, v44, v71
	v_add_f32_e32 v48, v46, v69
	v_add_f32_e32 v51, v48, v67
	v_add_f32_e32 v54, v51, v45
	v_add_f32_e32 v58, v65, v63
	v_add_f32_e32 v56, v54, v43
	v_add_f32_e32 v60, v58, v61
	v_cvt_pk_bf16_f32 v38, v38, v39
	v_cvt_pk_bf16_f32 v39, v40, v41
	v_add_f32_e32 v62, v60, v59
	ds_bpermute_b32 v40, v83, v56
	v_add_f32_e32 v64, v62, v57
	v_add_f32_e32 v66, v64, v55
	v_pk_add_f32 v[52:53], v[52:53], 1.0 op_sel_hi:[1,0] neg_lo:[1,0] neg_hi:[1,0]
	v_add_f32_e32 v68, v66, v49
	v_pk_mul_f32 v[52:53], v[52:53], v[84:85]
	v_pk_add_f32 v[84:85], v[86:87], 1.0 op_sel_hi:[1,0] neg_lo:[1,0] neg_hi:[1,0]
	v_add_f32_e32 v87, v68, v47
	ds_bpermute_b32 v41, v83, v87
	s_waitcnt lgkmcnt(1)
	v_add_f32_e32 v40, v56, v40
	v_cndmask_b32_e32 v70, v56, v40, vcc
	ds_bpermute_b32 v72, v90, v70
	v_cvt_pk_bf16_f32 v40, v52, v53
	s_waitcnt lgkmcnt(1)
	v_add_f32_e32 v41, v87, v41
	v_cndmask_b32_e32 v52, v87, v41, vcc
	ds_bpermute_b32 v53, v90, v52
	s_waitcnt lgkmcnt(1)
	v_add_f32_e32 v41, v70, v72
	v_cndmask_b32_e64 v70, v70, v41, s[6:7]
	ds_bpermute_b32 v86, v80, v70 offset:192
	v_pk_mul_f32 v[84:85], v[84:85], v[88:89]
	s_waitcnt lgkmcnt(1)
	v_add_f32_e32 v53, v52, v53
	v_cndmask_b32_e64 v52, v52, v53, s[6:7]
	v_sub_f32_e32 v70, v70, v56
	s_waitcnt lgkmcnt(0)
	v_add_f32_e32 v53, v52, v86
	ds_bpermute_b32 v52, v80, v52 offset:192
	v_sub_f32_e32 v53, v53, v87
	v_cvt_pk_bf16_f32 v41, v84, v85
	v_add_f32_e32 v83, v65, v53
	v_add_f32_e32 v42, v42, v70
	v_add_f32_e32 v58, v58, v53
	v_add_f32_e32 v60, v60, v53
	v_add_f32_e32 v84, v62, v53
	v_add_f32_e32 v85, v64, v53
	v_add_f32_e32 v88, v66, v53
	v_add_f32_e32 v89, v68, v53
	s_waitcnt lgkmcnt(0)
	v_pk_add_f32 v[52:53], v[86:87], v[52:53]
	v_add_f32_e32 v72, v77, v70
	v_sub_f32_e32 v42, v52, v42
	v_mul_f32_e32 v42, 0x3fb8aa3b, v42
	v_add_f32_e32 v44, v44, v70
	v_mul_f32_e32 v62, 0x3fb8aa3b, v77
	v_exp_f32_e32 v77, v42
	v_mul_f32_e32 v42, 0x3fb8aa3b, v73
	v_add_f32_e32 v46, v46, v70
	v_add_f32_e32 v48, v48, v70
	v_add_f32_e32 v51, v51, v70
	v_add_f32_e32 v54, v54, v70
	v_add_f32_e32 v56, v56, v70
	v_exp_f32_e32 v70, v42
	v_sub_f32_e32 v42, v52, v44
	v_exp_f32_e32 v74, v62
	v_sub_f32_e32 v62, v52, v72
	v_mul_f32_e32 v42, 0x3fb8aa3b, v42
	v_mul_f32_e32 v62, 0x3fb8aa3b, v62
	v_exp_f32_e32 v72, v42
	v_mul_f32_e32 v42, 0x3fb8aa3b, v71
	v_exp_f32_e32 v76, v62
	v_mul_f32_e32 v62, 0x3fb8aa3b, v75
	v_exp_f32_e32 v71, v42
	v_sub_f32_e32 v42, v52, v46
	v_mul_f32_e32 v46, 0x3fb8aa3b, v65
	v_exp_f32_e32 v75, v62
	v_exp_f32_e32 v62, v46
	v_sub_f32_e32 v46, v52, v83
	v_mul_f32_e32 v46, 0x3fb8aa3b, v46
	v_exp_f32_e32 v64, v46
	v_mul_f32_e32 v46, 0x3fb8aa3b, v63
	v_exp_f32_e32 v63, v46
	v_sub_f32_e32 v46, v52, v58
	v_mul_f32_e32 v46, 0x3fb8aa3b, v46
	v_exp_f32_e32 v65, v46
	v_mul_f32_e32 v46, 0x3fb8aa3b, v61
	v_exp_f32_e32 v58, v46
	v_sub_f32_e32 v46, v52, v60
	v_mul_f32_e32 v42, 0x3fb8aa3b, v42
	v_mul_f32_e32 v46, 0x3fb8aa3b, v46
	v_exp_f32_e32 v73, v42
	v_mul_f32_e32 v42, 0x3fb8aa3b, v69
	v_exp_f32_e32 v60, v46
	v_mul_f32_e32 v46, 0x3fb8aa3b, v59
	v_exp_f32_e32 v66, v42
	v_sub_f32_e32 v42, v52, v48
	v_exp_f32_e32 v59, v46
	v_sub_f32_e32 v46, v52, v84
	v_mul_f32_e32 v42, 0x3fb8aa3b, v42
	v_mul_f32_e32 v46, 0x3fb8aa3b, v46
	v_exp_f32_e32 v68, v42
	v_mul_f32_e32 v42, 0x3fb8aa3b, v67
	v_exp_f32_e32 v61, v46
	v_mul_f32_e32 v46, 0x3fb8aa3b, v57
	v_exp_f32_e32 v67, v42
	v_sub_f32_e32 v42, v52, v51
	v_sub_f32_e32 v44, v52, v54
	v_exp_f32_e32 v54, v46
	v_sub_f32_e32 v46, v52, v85
	v_mul_f32_e32 v42, 0x3fb8aa3b, v42
	v_mul_f32_e32 v46, 0x3fb8aa3b, v46
	v_exp_f32_e32 v69, v42
	v_mul_f32_e32 v42, 0x3fb8aa3b, v45
	v_sub_f32_e32 v45, v52, v56
	v_exp_f32_e32 v56, v46
	v_mul_f32_e32 v46, 0x3fb8aa3b, v55
	v_exp_f32_e32 v55, v46
	v_sub_f32_e32 v46, v52, v88
	v_mul_f32_e32 v46, 0x3fb8aa3b, v46
	v_exp_f32_e32 v57, v46
	v_mul_f32_e32 v46, 0x3fb8aa3b, v49
	v_sub_f32_e32 v48, v52, v89
	v_mul_f32_e32 v47, 0x3fb8aa3b, v47
	v_sub_f32_e32 v49, v52, v53
	v_mul_f32_e32 v43, 0x3fb8aa3b, v43
	v_exp_f32_e32 v46, v46
	v_mul_f32_e32 v48, 0x3fb8aa3b, v48
	v_exp_f32_e32 v47, v47
	v_mul_f32_e32 v49, 0x3fb8aa3b, v49
	v_exp_f32_e32 v42, v42
	v_mul_f32_e32 v44, 0x3fb8aa3b, v44
	v_exp_f32_e32 v43, v43
	v_mul_f32_e32 v45, 0x3fb8aa3b, v45
	v_exp_f32_e32 v48, v48
	v_exp_f32_e32 v49, v49
	v_exp_f32_e32 v44, v44
	v_exp_f32_e32 v45, v45
	v_pk_add_f32 v[54:55], v[54:55], 1.0 op_sel_hi:[1,0] neg_lo:[1,0] neg_hi:[1,0]
	v_pk_add_f32 v[70:71], v[70:71], 1.0 op_sel_hi:[1,0] neg_lo:[1,0] neg_hi:[1,0]
	v_pk_mul_f32 v[54:55], v[54:55], v[56:57]
	v_pk_add_f32 v[46:47], v[46:47], 1.0 op_sel_hi:[1,0] neg_lo:[1,0] neg_hi:[1,0]
	v_pk_mul_f32 v[70:71], v[70:71], v[72:73]
; __device__ __forceinline__ unsigned cvt_pk_bf16_c(float lo, float hi) { const f32x2_t v = {lo, hi}; return __builtin_bit_cast(unsigned, __builtin_convertvector(v, bf16x2_t)); }
;     __host__ __device__ __forceinline__ int item(int k) const { const int vv = vid + (k >> 3) * G; if (vv >= 256) return -1; const int pm = vv >> 2, p = vv & 3, j = k & 7; return (((pm >> 4) * 8 + 2 * p + (j >> 2)) << 6) + (pm & 15) * 4 + (j & 3); }
; __device__ __forceinline__ void store_wt(void* p, const u32x4 v) { asm volatile("global_store_dwordx4 %0, %1, off sc1\n\ts_nop 2" :: "v"(p), "v"(v) : "memory"); }
; template <class Ord> __device__ __forceinline__ void hgrn_h1(LAS unsigned char* lds, const _Float16* LF, const bf16_t* V, bf16_t* DS, float* DEC, const Ord& O, int tid) {
;     ...
;                     for (int i = 0; i < 8; ++i) kv[i] = (1.f - __expf(lf[ks][i])) * __expf(bl[ps] - b[ks][i]);
;                     kf[ps][ks] = pack8f(kv); } }
;             bf16_t* dsp = DS + (size_t)item * (HD * HD);
; #pragma unroll
;             for (int c = 0; c < 8; ++c) { f32x4 acc0 = (f32x4){0.f, 0.f, 0.f, 0.f}, acc1 = (f32x4){0.f, 0.f, 0.f, 0.f};
; #pragma unroll
;                 for (int ks = 0; ks < 2; ++ks) { const s16x4 lo = vl_tr_read(vl, 32 * ks + 8 * fq, c, lane), hi = vl_tr_read(vl, 32 * ks + 8 * fq + 4, c, lane);
;                     const bf16x8 vf = __builtin_shufflevector(lo, hi, 0, 1, 2, 3, 4, 5, 6, 7);
;                     acc0 = __builtin_amdgcn_mfma_f32_16x16x32_bf16(kf[0][ks], vf, acc0, 0, 0, 0);
;                     acc1 = __builtin_amdgcn_mfma_f32_16x16x32_bf16(kf[1][ks], vf, acc1, 0, 0, 0); }
;                 u32x2 o0, o1; o0.x = cvt_pk_bf16_c(acc0.x, acc0.y); o0.y = cvt_pk_bf16_c(acc0.z, acc0.w); o1.x = cvt_pk_bf16_c(acc1.x, acc1.y); o1.y = cvt_pk_bf16_c(acc1.z, acc1.w);
;                 const auto r0 = __builtin_amdgcn_permlane16_swap(o0.x, o1.x, false, false); const auto r1 = __builtin_amdgcn_permlane16_swap(o0.y, o1.y, false, false);
;                 u32x4 wv; wv.x = r0[0]; wv.y = r1[0]; wv.z = r0[1]; wv.w = r1[1];
;                 store_wt(dsp + (size_t)(16 * c + fr) * HD + 32 * wl + ((fq & 1) ? 16 + 4 * (fq - 1) : 4 * fq), wv); }
	v_pk_add_f32 v[66:67], v[66:67], 1.0 op_sel_hi:[1,0] neg_lo:[1,0] neg_hi:[1,0]
	v_pk_add_f32 v[42:43], v[42:43], 1.0 op_sel_hi:[1,0] neg_lo:[1,0] neg_hi:[1,0]
	v_pk_mul_f32 v[56:57], v[46:47], v[48:49]
	v_cvt_pk_bf16_f32 v48, v54, v55
	v_bfe_u32 v51, v79, 2, 2
	v_lshlrev_b32_e32 v55, 3, v79
	v_pk_add_f32 v[74:75], v[74:75], 1.0 op_sel_hi:[1,0] neg_lo:[1,0] neg_hi:[1,0]
	v_pk_mul_f32 v[66:67], v[66:67], v[68:69]
	v_pk_mul_f32 v[68:69], v[42:43], v[44:45]
	v_cvt_pk_bf16_f32 v43, v70, v71
	v_lshlrev_b32_e32 v54, 1, v0
	v_and_b32_e32 v70, 8, v55
	v_or_b32_e32 v55, v82, v51
	v_pk_mul_f32 v[74:75], v[74:75], v[76:77]
	v_cvt_pk_bf16_f32 v45, v68, v69
	v_lshlrev_b32_e32 v68, 2, v51
	v_and_b32_e32 v69, 2, v54
	v_lshlrev_b32_e32 v72, 8, v55
	v_or_b32_e32 v55, 4, v82
	v_cvt_pk_bf16_f32 v42, v74, v75
	v_pk_add_f32 v[58:59], v[58:59], 1.0 op_sel_hi:[1,0] neg_lo:[1,0] neg_hi:[1,0]
	v_bfe_u32 v53, v79, 1, 1
	v_or_b32_e32 v54, v69, v68
	v_bfe_u32 v74, v55, 2, 2
	v_pk_mul_f32 v[58:59], v[58:59], v[60:61]
	v_cvt_pk_bf16_f32 v49, v56, v57
	v_add_u32_e32 v71, s8, v70
	v_or_b32_e32 v54, v54, v53
	v_or_b32_e32 v56, v55, v51
	v_bitop3_b32 v55, v74, v53, v68 bitop3:0x36
	v_cvt_pk_bf16_f32 v47, v58, v59
	v_lshl_add_u32 v58, v54, 4, v71
	v_lshlrev_b32_e32 v73, 8, v56
	v_lshl_add_u32 v55, v55, 4, s8
	v_or_b32_e32 v59, v91, v51
	v_add_u32_e32 v54, v58, v72
	v_add3_u32 v56, v55, v73, v70
	v_lshlrev_b32_e32 v75, 8, v59
	v_add_u32_e32 v59, 36, v82
	v_cvt_pk_bf16_f32 v44, v66, v67
	ds_read_b64_tr_b16 v[54:55], v54 offset:33792
	ds_read_b64_tr_b16 v[56:57], v56 offset:33792
	v_bfe_u32 v76, v59, 2, 2
	v_or_b32_e32 v51, v59, v51
	v_bitop3_b32 v59, v76, v53, v68 bitop3:0x36
	v_pk_add_f32 v[62:63], v[62:63], 1.0 op_sel_hi:[1,0] neg_lo:[1,0] neg_hi:[1,0]
	v_lshlrev_b32_e32 v51, 8, v51
	v_lshl_add_u32 v59, v59, 4, s8
	v_pk_mul_f32 v[62:63], v[62:63], v[64:65]
	v_add_u32_e32 v58, v58, v75
	v_add3_u32 v60, v59, v51, v70
	v_cvt_pk_bf16_f32 v46, v62, v63
	ds_read_b64_tr_b16 v[58:59], v58 offset:33792
	ds_read_b64_tr_b16 v[60:61], v60 offset:33792
	s_waitcnt lgkmcnt(2)
	v_mfma_f32_16x16x32_bf16 v[62:65], v[34:37], v[54:57], 0
	v_and_b32_e32 v66, 16, v79
	v_lshlrev_b32_e32 v0, 2, v0
	s_lshl_b64 s[6:7], s[44:45], 15
	v_mfma_f32_16x16x32_bf16 v[54:57], v[42:45], v[54:57], 0
	v_add_u32_e32 v67, 12, v0
	v_cmp_eq_u32_e32 vcc, 0, v66
	s_add_u32 s6, s15, s6
	s_waitcnt lgkmcnt(0)
	v_mfma_f32_16x16x32_bf16 v[62:65], v[38:41], v[58:61], v[62:65]
	v_cndmask_b32_e32 v66, v67, v0, vcc
	s_addc_u32 s7, s16, s7
	v_ashrrev_i32_e32 v67, 31, v66
	v_mfma_f32_16x16x32_bf16 v[54:57], v[46:49], v[58:61], v[54:57]
	v_lshl_add_u64 v[66:67], v[66:67], 1, s[6:7]
	v_lshlrev_b32_e32 v0, 6, v81
	s_nop 1
	v_cvt_pk_bf16_f32 v58, v62, v63
	v_cvt_pk_bf16_f32 v59, v64, v65
	s_mov_b64 s[6:7], 0x1000
	s_nop 0
	v_cvt_pk_bf16_f32 v60, v54, v55
	v_lshl_add_u64 v[54:55], v[66:67], 0, v[0:1]
	v_or_b32_e32 v0, 2, v53
	v_cvt_pk_bf16_f32 v61, v56, v57
	v_permlane16_swap_b32_e32 v58, v60
	v_bitop3_b32 v56, v69, v0, v68 bitop3:0x36
	v_bitop3_b32 v57, v74, v0, v68 bitop3:0x36
	v_permlane16_swap_b32_e32 v59, v61
	global_store_dwordx4 v[54:55], v[58:61], off sc1
	s_nop 2
	v_lshl_add_u32 v60, v56, 4, v71
	v_lshl_add_u32 v57, v57, 4, s8
	v_add_u32_e32 v56, v60, v72
	v_add3_u32 v58, v57, v73, v70
	ds_read_b64_tr_b16 v[56:57], v56 offset:33792
	ds_read_b64_tr_b16 v[58:59], v58 offset:33792
	v_bitop3_b32 v0, v76, v0, v68 bitop3:0x36
	v_add_u32_e32 v60, v60, v75
	v_lshl_add_u32 v0, v0, 4, s8
	v_add3_u32 v0, v0, v51, v70
	ds_read_b64_tr_b16 v[60:61], v60 offset:33792
	ds_read_b64_tr_b16 v[62:63], v0 offset:33792
	s_waitcnt lgkmcnt(2)
	v_mfma_f32_16x16x32_bf16 v[64:67], v[34:37], v[56:59], 0
	v_or_b32_e32 v0, 4, v53
	v_cmp_gt_u32_e32 vcc, 16, v79
	v_mfma_f32_16x16x32_bf16 v[56:59], v[42:45], v[56:59], 0
	s_waitcnt lgkmcnt(0)
	v_mfma_f32_16x16x32_bf16 v[64:67], v[38:41], v[60:63], v[64:67]
	v_mfma_f32_16x16x32_bf16 v[56:59], v[46:49], v[60:63], v[56:59]
	s_nop 6
	v_cvt_pk_bf16_f32 v60, v64, v65
	v_cvt_pk_bf16_f32 v61, v66, v67
	v_cvt_pk_bf16_f32 v62, v56, v57
	v_cvt_pk_bf16_f32 v63, v58, v59
	v_lshl_add_u64 v[56:57], v[54:55], 0, s[6:7]
	v_permlane16_swap_b32_e32 v60, v62
	v_permlane16_swap_b32_e32 v61, v63
	global_store_dwordx4 v[56:57], v[60:63], off sc1
	s_nop 2
	v_bitop3_b32 v56, v69, v0, v68 bitop3:0x36
	v_bitop3_b32 v57, v74, v0, v68 bitop3:0x36
	v_lshl_add_u32 v60, v56, 4, v71
	v_lshl_add_u32 v57, v57, 4, s8
	v_add_u32_e32 v56, v60, v72
	v_add3_u32 v58, v57, v73, v70
	ds_read_b64_tr_b16 v[56:57], v56 offset:33792
	ds_read_b64_tr_b16 v[58:59], v58 offset:33792
	v_bitop3_b32 v0, v76, v0, v68 bitop3:0x36
	v_add_u32_e32 v60, v60, v75
	v_lshl_add_u32 v0, v0, 4, s8
	v_add3_u32 v0, v0, v51, v70
	ds_read_b64_tr_b16 v[60:61], v60 offset:33792
	ds_read_b64_tr_b16 v[62:63], v0 offset:33792
	s_waitcnt lgkmcnt(2)
	v_mfma_f32_16x16x32_bf16 v[64:67], v[34:37], v[56:59], 0
	s_mov_b64 s[6:7], 0x2000
	v_or_b32_e32 v0, 6, v53
	v_mfma_f32_16x16x32_bf16 v[56:59], v[42:45], v[56:59], 0
	s_waitcnt lgkmcnt(0)
	v_mfma_f32_16x16x32_bf16 v[64:67], v[38:41], v[60:63], v[64:67]
	v_mfma_f32_16x16x32_bf16 v[56:59], v[46:49], v[60:63], v[56:59]
	s_nop 6
	v_cvt_pk_bf16_f32 v60, v64, v65
	v_cvt_pk_bf16_f32 v61, v66, v67
	v_cvt_pk_bf16_f32 v62, v56, v57
	v_cvt_pk_bf16_f32 v63, v58, v59
	v_lshl_add_u64 v[56:57], v[54:55], 0, s[6:7]
	v_permlane16_swap_b32_e32 v60, v62
	v_permlane16_swap_b32_e32 v61, v63
	global_store_dwordx4 v[56:57], v[60:63], off sc1
	s_nop 2
	v_bitop3_b32 v56, v69, v0, v68 bitop3:0x36
	v_bitop3_b32 v57, v74, v0, v68 bitop3:0x36
	v_lshl_add_u32 v60, v56, 4, v71
	v_lshl_add_u32 v57, v57, 4, s8
	v_add_u32_e32 v56, v60, v72
	v_add3_u32 v58, v57, v73, v70
	ds_read_b64_tr_b16 v[56:57], v56 offset:33792
	ds_read_b64_tr_b16 v[58:59], v58 offset:33792
	v_bitop3_b32 v0, v76, v0, v68 bitop3:0x36
	v_add_u32_e32 v60, v60, v75
	v_lshl_add_u32 v0, v0, 4, s8
	v_add3_u32 v0, v0, v51, v70
	ds_read_b64_tr_b16 v[60:61], v60 offset:33792
	ds_read_b64_tr_b16 v[62:63], v0 offset:33792
	s_waitcnt lgkmcnt(2)
; __device__ __forceinline__ unsigned cvt_pk_bf16_c(float lo, float hi) { const f32x2_t v = {lo, hi}; return __builtin_bit_cast(unsigned, __builtin_convertvector(v, bf16x2_t)); }
;     __host__ __device__ __forceinline__ int item(int k) const { const int vv = vid + (k >> 3) * G; if (vv >= 256) return -1; const int pm = vv >> 2, p = vv & 3, j = k & 7; return (((pm >> 4) * 8 + 2 * p + (j >> 2)) << 6) + (pm & 15) * 4 + (j & 3); }
; __device__ __forceinline__ void store_wt(void* p, const u32x4 v) { asm volatile("global_store_dwordx4 %0, %1, off sc1\n\ts_nop 2" :: "v"(p), "v"(v) : "memory"); }
; template <class Ord> __device__ __forceinline__ void hgrn_h1(LAS unsigned char* lds, const _Float16* LF, const bf16_t* V, bf16_t* DS, float* DEC, const Ord& O, int tid) {
;     ...
; #pragma unroll
;             for (int c = 0; c < 8; ++c) { f32x4 acc0 = (f32x4){0.f, 0.f, 0.f, 0.f}, acc1 = (f32x4){0.f, 0.f, 0.f, 0.f};
; #pragma unroll
;                 for (int ks = 0; ks < 2; ++ks) { const s16x4 lo = vl_tr_read(vl, 32 * ks + 8 * fq, c, lane), hi = vl_tr_read(vl, 32 * ks + 8 * fq + 4, c, lane);
;                     const bf16x8 vf = __builtin_shufflevector(lo, hi, 0, 1, 2, 3, 4, 5, 6, 7);
;                     acc0 = __builtin_amdgcn_mfma_f32_16x16x32_bf16(kf[0][ks], vf, acc0, 0, 0, 0);
;                     acc1 = __builtin_amdgcn_mfma_f32_16x16x32_bf16(kf[1][ks], vf, acc1, 0, 0, 0); }
;                 u32x2 o0, o1; o0.x = cvt_pk_bf16_c(acc0.x, acc0.y); o0.y = cvt_pk_bf16_c(acc0.z, acc0.w); o1.x = cvt_pk_bf16_c(acc1.x, acc1.y); o1.y = cvt_pk_bf16_c(acc1.z, acc1.w);
;                 const auto r0 = __builtin_amdgcn_permlane16_swap(o0.x, o1.x, false, false); const auto r1 = __builtin_amdgcn_permlane16_swap(o0.y, o1.y, false, false);
;                 u32x4 wv; wv.x = r0[0]; wv.y = r1[0]; wv.z = r0[1]; wv.w = r1[1];
;                 store_wt(dsp + (size_t)(16 * c + fr) * HD + 32 * wl + ((fq & 1) ? 16 + 4 * (fq - 1) : 4 * fq), wv); }
;             if (fq == 0) { __hip_atomic_store(&DEC[(size_t)item * HD + 32 * wl + fr], __expf(bl[0]), __ATOMIC_RELAXED, __HIP_MEMORY_SCOPE_AGENT); __hip_atomic_store(&DEC[(size_t)item * HD + 32 * wl + 16 + fr], __expf(bl[1]), __ATOMIC_RELAXED, __HIP_MEMORY_SCOPE_AGENT); }
	v_mfma_f32_16x16x32_bf16 v[64:67], v[34:37], v[56:59], 0
	s_mov_b64 s[6:7], 0x3000
	v_or_b32_e32 v0, 8, v53
	v_mfma_f32_16x16x32_bf16 v[56:59], v[42:45], v[56:59], 0
	s_waitcnt lgkmcnt(0)
	v_mfma_f32_16x16x32_bf16 v[64:67], v[38:41], v[60:63], v[64:67]
	v_mfma_f32_16x16x32_bf16 v[56:59], v[46:49], v[60:63], v[56:59]
	s_nop 6
	v_cvt_pk_bf16_f32 v60, v64, v65
	v_cvt_pk_bf16_f32 v61, v66, v67
	v_cvt_pk_bf16_f32 v62, v56, v57
	v_cvt_pk_bf16_f32 v63, v58, v59
	v_lshl_add_u64 v[56:57], v[54:55], 0, s[6:7]
	v_permlane16_swap_b32_e32 v60, v62
	v_permlane16_swap_b32_e32 v61, v63
	global_store_dwordx4 v[56:57], v[60:63], off sc1
	s_nop 2
	v_bitop3_b32 v56, v69, v0, v68 bitop3:0x36
	v_bitop3_b32 v57, v74, v0, v68 bitop3:0x36
	v_lshl_add_u32 v60, v56, 4, v71
	v_lshl_add_u32 v57, v57, 4, s8
	v_add_u32_e32 v56, v60, v72
	v_add3_u32 v58, v57, v73, v70
	ds_read_b64_tr_b16 v[56:57], v56 offset:33792
	ds_read_b64_tr_b16 v[58:59], v58 offset:33792
	v_bitop3_b32 v0, v76, v0, v68 bitop3:0x36
	v_add_u32_e32 v60, v60, v75
	v_lshl_add_u32 v0, v0, 4, s8
	v_add3_u32 v0, v0, v51, v70
	ds_read_b64_tr_b16 v[60:61], v60 offset:33792
	ds_read_b64_tr_b16 v[62:63], v0 offset:33792
	s_waitcnt lgkmcnt(2)
	v_mfma_f32_16x16x32_bf16 v[64:67], v[34:37], v[56:59], 0
	s_mov_b64 s[6:7], 0x4000
	v_or_b32_e32 v0, 10, v53
	v_mfma_f32_16x16x32_bf16 v[56:59], v[42:45], v[56:59], 0
	s_waitcnt lgkmcnt(0)
	v_mfma_f32_16x16x32_bf16 v[64:67], v[38:41], v[60:63], v[64:67]
	v_mfma_f32_16x16x32_bf16 v[56:59], v[46:49], v[60:63], v[56:59]
	s_nop 6
	v_cvt_pk_bf16_f32 v60, v64, v65
	v_cvt_pk_bf16_f32 v61, v66, v67
	v_cvt_pk_bf16_f32 v62, v56, v57
	v_cvt_pk_bf16_f32 v63, v58, v59
	v_lshl_add_u64 v[56:57], v[54:55], 0, s[6:7]
	v_permlane16_swap_b32_e32 v60, v62
	v_permlane16_swap_b32_e32 v61, v63
	global_store_dwordx4 v[56:57], v[60:63], off sc1
	s_nop 2
	v_bitop3_b32 v56, v69, v0, v68 bitop3:0x36
	v_bitop3_b32 v57, v74, v0, v68 bitop3:0x36
	v_lshl_add_u32 v60, v56, 4, v71
	v_lshl_add_u32 v57, v57, 4, s8
	v_add_u32_e32 v56, v60, v72
	v_add3_u32 v58, v57, v73, v70
	ds_read_b64_tr_b16 v[56:57], v56 offset:33792
	ds_read_b64_tr_b16 v[58:59], v58 offset:33792
	v_bitop3_b32 v0, v76, v0, v68 bitop3:0x36
	v_add_u32_e32 v60, v60, v75
	v_lshl_add_u32 v0, v0, 4, s8
	v_add3_u32 v0, v0, v51, v70
	ds_read_b64_tr_b16 v[60:61], v60 offset:33792
	ds_read_b64_tr_b16 v[62:63], v0 offset:33792
	s_waitcnt lgkmcnt(2)
	v_mfma_f32_16x16x32_bf16 v[64:67], v[34:37], v[56:59], 0
	s_mov_b64 s[6:7], 0x5000
	v_or_b32_e32 v0, 12, v53
	v_mfma_f32_16x16x32_bf16 v[56:59], v[42:45], v[56:59], 0
	s_waitcnt lgkmcnt(0)
	v_mfma_f32_16x16x32_bf16 v[64:67], v[38:41], v[60:63], v[64:67]
	v_mfma_f32_16x16x32_bf16 v[56:59], v[46:49], v[60:63], v[56:59]
	s_nop 6
	v_cvt_pk_bf16_f32 v60, v64, v65
	v_cvt_pk_bf16_f32 v61, v66, v67
	v_cvt_pk_bf16_f32 v62, v56, v57
	v_cvt_pk_bf16_f32 v63, v58, v59
	v_lshl_add_u64 v[56:57], v[54:55], 0, s[6:7]
	v_permlane16_swap_b32_e32 v60, v62
	v_permlane16_swap_b32_e32 v61, v63
	global_store_dwordx4 v[56:57], v[60:63], off sc1
	s_nop 2
	v_bitop3_b32 v56, v69, v0, v68 bitop3:0x36
	v_bitop3_b32 v57, v74, v0, v68 bitop3:0x36
	v_lshl_add_u32 v60, v56, 4, v71
	v_lshl_add_u32 v57, v57, 4, s8
	v_add_u32_e32 v56, v60, v72
	v_add3_u32 v58, v57, v73, v70
	ds_read_b64_tr_b16 v[56:57], v56 offset:33792
	ds_read_b64_tr_b16 v[58:59], v58 offset:33792
	v_bitop3_b32 v0, v76, v0, v68 bitop3:0x36
	v_add_u32_e32 v60, v60, v75
	v_lshl_add_u32 v0, v0, 4, s8
	v_add3_u32 v0, v0, v51, v70
	ds_read_b64_tr_b16 v[60:61], v60 offset:33792
	ds_read_b64_tr_b16 v[62:63], v0 offset:33792
	s_waitcnt lgkmcnt(2)
	v_mfma_f32_16x16x32_bf16 v[64:67], v[34:37], v[56:59], 0
	s_mov_b64 s[6:7], 0x6000
	v_or_b32_e32 v0, 14, v53
	v_bitop3_b32 v53, v69, v0, v68 bitop3:0x36
	v_mfma_f32_16x16x32_bf16 v[56:59], v[42:45], v[56:59], 0
	v_lshl_add_u32 v53, v53, 4, v71
	s_waitcnt lgkmcnt(0)
	v_mfma_f32_16x16x32_bf16 v[64:67], v[38:41], v[60:63], v[64:67]
	v_mfma_f32_16x16x32_bf16 v[56:59], v[46:49], v[60:63], v[56:59]
	s_nop 6
	v_cvt_pk_bf16_f32 v60, v64, v65
	v_cvt_pk_bf16_f32 v61, v66, v67
	v_cvt_pk_bf16_f32 v62, v56, v57
	v_cvt_pk_bf16_f32 v63, v58, v59
	v_lshl_add_u64 v[56:57], v[54:55], 0, s[6:7]
	v_permlane16_swap_b32_e32 v60, v62
	v_permlane16_swap_b32_e32 v61, v63
	global_store_dwordx4 v[56:57], v[60:63], off sc1
	s_nop 2
	v_bitop3_b32 v57, v74, v0, v68 bitop3:0x36
	v_lshl_add_u32 v57, v57, 4, s8
	v_add_u32_e32 v56, v53, v72
	v_add3_u32 v58, v57, v73, v70
	ds_read_b64_tr_b16 v[56:57], v56 offset:33792
	ds_read_b64_tr_b16 v[58:59], v58 offset:33792
	v_bitop3_b32 v0, v76, v0, v68 bitop3:0x36
	v_add_u32_e32 v53, v53, v75
	v_lshl_add_u32 v0, v0, 4, s8
	v_add3_u32 v0, v0, v51, v70
	ds_read_b64_tr_b16 v[60:61], v53 offset:33792
	ds_read_b64_tr_b16 v[62:63], v0 offset:33792
	s_waitcnt lgkmcnt(2)
	v_mfma_f32_16x16x32_bf16 v[34:37], v[34:37], v[56:59], 0
	s_mov_b64 s[6:7], 0x7000
	v_mfma_f32_16x16x32_bf16 v[42:45], v[42:45], v[56:59], 0
	s_waitcnt lgkmcnt(0)
	v_mfma_f32_16x16x32_bf16 v[34:37], v[38:41], v[60:63], v[34:37]
	v_mfma_f32_16x16x32_bf16 v[38:41], v[46:49], v[60:63], v[42:45]
	s_nop 6
	v_cvt_pk_bf16_f32 v34, v34, v35
	v_cvt_pk_bf16_f32 v35, v36, v37
	v_cvt_pk_bf16_f32 v36, v38, v39
	v_cvt_pk_bf16_f32 v37, v40, v41
	s_nop 0
	v_permlane16_swap_b32_e32 v34, v36
	v_permlane16_swap_b32_e32 v35, v37
	v_lshl_add_u64 v[38:39], v[54:55], 0, s[6:7]
	global_store_dwordx4 v[38:39], v[34:37], off sc1
	s_nop 2
	s_and_saveexec_b64 s[6:7], vcc
	s_cbranch_execz .LBB0_638
	v_mul_f32_e32 v0, 0x3fb8aa3b, v50
	v_exp_f32_e32 v0, v0
	v_mul_f32_e32 v34, 0x3fb8aa3b, v52
	s_lshl_b64 s[22:23], s[44:45], 9
	v_exp_f32_e32 v34, v34
	s_add_u32 s22, s17, s22
	s_addc_u32 s23, s18, s23
	global_store_dword v80, v0, s[22:23] sc1
	global_store_dword v80, v34, s[22:23] offset:64 sc1
	s_branch .LBB0_638

; #define LAS __attribute__((address_space(3)))
; __device__ __forceinline__ void hgrn_h2(LAS unsigned char* lds, bf16_t* DS, const float* DEC, int cid, int G, int tid) {
;     if (tid < 256) { const int lane = tid & 63; LAS float* DL = (LAS float*)(lds + (tid >> 6) * 32768);
;       const bool team = (G == 256); const int vidq = 32 * (cid & 7) + (cid >> 3), pmq = vidq >> 2, pq = vidq & 3;
;       const int g0 = team ? (((pmq >> 4) * 8 + 2 * pq) << 11) + 256 * (pmq & 15) + tid : cid * 256 + tid;
;       for (int g = g0; g < NB * NH * HD * (HD / 8); g += (team ? NB * NH * HD * (HD / 8) : G * 256)) {
;         const int bh = g >> 11, v = (g >> 4) & 127, d = (g & 15) * 8;
;         bf16_t* p = DS + (size_t)bh * NCH * (HD * HD) + (size_t)v * HD + d; const float* dp = DEC + (size_t)bh * NCH * HD;
;         float S[8];
; #pragma unroll
;         for (int j = 0; j < 8; ++j) S[j] = 0.f;
;         u32x4 raw[32];
; #pragma unroll
;         for (int j = 0; j < 32; ++j) raw[j] = *(const u32x4*)(p + (size_t)j * (HD * HD));
.LBB0_821:
	v_ashrrev_i32_e32 v34, 11, v232
	v_lshlrev_b32_e32 v0, 3, v232
	v_ashrrev_i32_e32 v35, 31, v34
	v_and_b32_e32 v46, 0x78, v0
	v_lshlrev_b64 v[2:3], 21, v[34:35]
	v_lshlrev_b32_e32 v0, 4, v232
	v_lshl_add_u64 v[2:3], s[10:11], 0, v[2:3]
	v_and_b32_e32 v0, 0x7f00, v0
	v_lshl_add_u64 v[2:3], v[2:3], 0, v[0:1]
	v_lshlrev_b32_e32 v0, 1, v46
	v_lshl_add_u64 v[150:151], v[2:3], 0, v[0:1]
	s_mov_b32 s2, 0x8000
	v_add_co_u32_e32 v2, vcc, s2, v150
	s_mov_b32 s2, 0x18000
	s_nop 0
	v_addc_co_u32_e32 v3, vcc, 0, v151, vcc
	v_add_co_u32_e32 v4, vcc, s66, v150
	v_lshlrev_b64 v[34:35], 15, v[34:35]
	s_nop 0
	v_addc_co_u32_e32 v5, vcc, 0, v151, vcc
	v_add_co_u32_e32 v6, vcc, s2, v150
	s_mov_b32 s2, 0x20000
	s_nop 0
	v_addc_co_u32_e32 v7, vcc, 0, v151, vcc
	v_add_co_u32_e32 v8, vcc, s2, v150
	s_mov_b32 s2, 0x28000
	s_nop 0
	v_addc_co_u32_e32 v9, vcc, 0, v151, vcc
	v_add_co_u32_e32 v10, vcc, s2, v150
	s_mov_b32 s2, 0x30000
	s_nop 0
	v_addc_co_u32_e32 v11, vcc, 0, v151, vcc
	v_add_co_u32_e32 v12, vcc, s2, v150
	s_mov_b32 s2, 0x38000
	s_nop 0
	v_addc_co_u32_e32 v13, vcc, 0, v151, vcc
	v_add_co_u32_e32 v14, vcc, s2, v150
	s_mov_b32 s2, 0x40000
	s_nop 0
	v_addc_co_u32_e32 v15, vcc, 0, v151, vcc
	v_add_co_u32_e32 v16, vcc, s2, v150
	s_mov_b32 s2, 0x48000
	s_nop 0
	v_addc_co_u32_e32 v17, vcc, 0, v151, vcc
	v_add_co_u32_e32 v18, vcc, s2, v150
	s_mov_b32 s2, 0x50000
	s_nop 0
	v_addc_co_u32_e32 v19, vcc, 0, v151, vcc
	v_add_co_u32_e32 v20, vcc, s2, v150
	s_mov_b32 s2, 0x58000
	s_nop 0
	v_addc_co_u32_e32 v21, vcc, 0, v151, vcc
	v_add_co_u32_e32 v22, vcc, s2, v150
	s_mov_b32 s2, 0x60000
	s_nop 0
	v_addc_co_u32_e32 v23, vcc, 0, v151, vcc
	v_add_co_u32_e32 v24, vcc, s2, v150
	s_mov_b32 s2, 0x68000
	s_nop 0
	v_addc_co_u32_e32 v25, vcc, 0, v151, vcc
	v_add_co_u32_e32 v26, vcc, s2, v150
	s_mov_b32 s2, 0x70000
	s_nop 0
	v_addc_co_u32_e32 v27, vcc, 0, v151, vcc
	v_add_co_u32_e32 v28, vcc, s2, v150
	s_mov_b32 s2, 0x78000
	s_nop 0
	v_addc_co_u32_e32 v29, vcc, 0, v151, vcc
	v_add_co_u32_e32 v30, vcc, s2, v150
	s_mov_b32 s2, 0x80000
	s_nop 0
	v_addc_co_u32_e32 v31, vcc, 0, v151, vcc
	v_add_co_u32_e32 v32, vcc, s2, v150
	s_mov_b32 s2, 0x88000
	s_nop 0
	v_addc_co_u32_e32 v33, vcc, 0, v151, vcc
	v_add_co_u32_e32 v36, vcc, s2, v150
	s_mov_b32 s2, 0x90000
	s_nop 0
	v_addc_co_u32_e32 v37, vcc, 0, v151, vcc
	v_add_co_u32_e32 v38, vcc, s2, v150
	s_mov_b32 s2, 0x98000
	s_nop 0
	v_addc_co_u32_e32 v39, vcc, 0, v151, vcc
	v_add_co_u32_e32 v40, vcc, s2, v150
	s_mov_b32 s2, 0xa0000
	s_nop 0
	v_addc_co_u32_e32 v41, vcc, 0, v151, vcc
	v_add_co_u32_e32 v42, vcc, s2, v150
	s_mov_b32 s2, 0xa8000
	s_nop 0
	v_addc_co_u32_e32 v43, vcc, 0, v151, vcc
	v_add_co_u32_e32 v44, vcc, s2, v150
	s_mov_b32 s2, 0xb0000
	s_nop 0
	v_addc_co_u32_e32 v45, vcc, 0, v151, vcc
	v_add_co_u32_e32 v48, vcc, s2, v150
	s_mov_b32 s2, 0xb8000
	s_nop 0
	v_addc_co_u32_e32 v49, vcc, 0, v151, vcc
	v_add_co_u32_e32 v138, vcc, s2, v150
	s_mov_b32 s2, 0xc0000
	s_nop 0
	v_addc_co_u32_e32 v139, vcc, 0, v151, vcc
	v_add_co_u32_e32 v140, vcc, s2, v150
	s_mov_b32 s2, 0xc8000
	s_nop 0
	v_addc_co_u32_e32 v141, vcc, 0, v151, vcc
	v_add_co_u32_e32 v142, vcc, s2, v150
	s_mov_b32 s2, 0xd0000
	s_nop 0
	v_addc_co_u32_e32 v143, vcc, 0, v151, vcc
	v_add_co_u32_e32 v144, vcc, s2, v150
	s_mov_b32 s2, 0xd8000
	s_nop 0
	v_addc_co_u32_e32 v145, vcc, 0, v151, vcc
	v_add_co_u32_e32 v152, vcc, s2, v150
	s_mov_b32 s2, 0xe0000
	s_nop 0
	v_addc_co_u32_e32 v153, vcc, 0, v151, vcc
	v_add_co_u32_e32 v154, vcc, s2, v150
	s_mov_b32 s2, 0xe8000
	s_nop 0
	v_addc_co_u32_e32 v155, vcc, 0, v151, vcc
	v_add_co_u32_e32 v156, vcc, s2, v150
	s_mov_b32 s2, 0xf0000
	s_nop 0
	v_addc_co_u32_e32 v157, vcc, 0, v151, vcc
	v_add_co_u32_e32 v158, vcc, s2, v150
	s_mov_b32 s2, 0xf8000
	s_nop 0
	v_addc_co_u32_e32 v159, vcc, 0, v151, vcc
	v_add_co_u32_e32 v160, vcc, s2, v150
	v_lshl_add_u64 v[162:163], v[148:149], 0, v[34:35]
	s_nop 0
	v_addc_co_u32_e32 v161, vcc, 0, v151, vcc
	s_movk_i32 s2, 0x1000
	v_add_co_u32_e32 v172, vcc, s2, v162
	global_load_dwordx4 v[54:57], v[150:151], off
	global_load_dwordx4 v[62:65], v[2:3], off
	global_load_dwordx4 v[70:73], v[4:5], off
	global_load_dwordx4 v[78:81], v[6:7], off
	global_load_dwordx4 v[86:89], v[8:9], off
	global_load_dwordx4 v[94:97], v[10:11], off
	global_load_dwordx4 v[102:105], v[12:13], off
	global_load_dwordx4 v[110:113], v[14:15], off
	global_load_dwordx4 v[118:121], v[16:17], off
	global_load_dwordx4 v[126:129], v[18:19], off
	global_load_dwordx4 v[134:137], v[20:21], off
	global_load_dwordx4 v[130:133], v[22:23], off
	global_load_dwordx4 v[122:125], v[24:25], off
	global_load_dwordx4 v[114:117], v[26:27], off
	global_load_dwordx4 v[106:109], v[28:29], off
	global_load_dwordx4 v[98:101], v[30:31], off
	global_load_dwordx4 v[90:93], v[32:33], off
	global_load_dwordx4 v[82:85], v[36:37], off
	global_load_dwordx4 v[74:77], v[38:39], off
	global_load_dwordx4 v[66:69], v[40:41], off
	global_load_dwordx4 v[58:61], v[42:43], off
	global_load_dwordx4 v[50:53], v[44:45], off
	s_nop 0
	global_load_dwordx4 v[42:45], v[48:49], off
	global_load_dwordx4 v[38:41], v[138:139], off
	global_load_dwordx4 v[30:33], v[140:141], off
	global_load_dwordx4 v[26:29], v[142:143], off
	global_load_dwordx4 v[22:25], v[144:145], off
	global_load_dwordx4 v[18:21], v[152:153], off
	global_load_dwordx4 v[14:17], v[154:155], off
	global_load_dwordx4 v[10:13], v[156:157], off
	global_load_dwordx4 v[6:9], v[158:159], off
	global_load_dwordx4 v[2:5], v[160:161], off
	v_addc_co_u32_e32 v173, vcc, 0, v163, vcc
	v_add_co_u32_e32 v176, vcc, s65, v162
	s_waitcnt lgkmcnt(0)
; #define LAS __attribute__((address_space(3)))
; __device__ __forceinline__ void hgrn_h2(LAS unsigned char* lds, bf16_t* DS, const float* DEC, int cid, int G, int tid) {
;     ...
;         for (int j = 0; j < 32; ++j) raw[j] = *(const u32x4*)(p + (size_t)j * (HD * HD));
;         asm volatile("s_waitcnt lgkmcnt(0)" ::: "memory");
; #pragma unroll
;         for (int h = 0; h < 4; ++h) { f32x4 t[8];
; #pragma unroll
;             for (int j = 0; j < 8; ++j) t[j] = *(const f32x4*)(dp + 4 * (lane + 64 * (8 * h + j)));
; #pragma unroll
;             for (int j = 0; j < 8; ++j) *(LAS f32x4*)(DL + 4 * (lane + 64 * (8 * h + j))) = t[j]; }
	v_add_u32_e32 v0, v233, v146
	s_nop 0
	v_addc_co_u32_e32 v177, vcc, 0, v163, vcc
	v_add_co_u32_e32 v178, vcc, s80, v162
	s_mov_b64 s[6:7], 0x100000
	s_nop 0
	v_addc_co_u32_e32 v179, vcc, 0, v163, vcc
	v_add_co_u32_e32 v192, vcc, s60, v162
	s_mov_b32 s2, 0
	s_nop 0
	v_addc_co_u32_e32 v193, vcc, 0, v163, vcc
	v_add_co_u32_e32 v208, vcc, s82, v162
	s_mov_b64 s[14:15], -1
	s_nop 0
	v_addc_co_u32_e32 v209, vcc, 0, v163, vcc
	v_add_co_u32_e32 v212, vcc, s71, v162
	s_nop 1
	v_addc_co_u32_e32 v213, vcc, 0, v163, vcc
	v_add_co_u32_e32 v34, vcc, s81, v162
	s_nop 1
	v_addc_co_u32_e32 v35, vcc, 0, v163, vcc
	global_load_dwordx4 v[138:141], v[162:163], off
	global_load_dwordx4 v[142:145], v[162:163], off offset:1024
	global_load_dwordx4 v[152:155], v[162:163], off offset:2048
	global_load_dwordx4 v[156:159], v[162:163], off offset:3072
	s_nop 0
	global_load_dwordx4 v[160:163], v[176:177], off offset:-4096
	global_load_dwordx4 v[164:167], v[172:173], off offset:1024
	global_load_dwordx4 v[168:171], v[172:173], off offset:2048
	s_nop 0
	global_load_dwordx4 v[172:175], v[172:173], off offset:3072
	s_waitcnt vmcnt(7)
	ds_write_b128 v0, v[138:141]
	s_waitcnt vmcnt(6)
	ds_write_b128 v0, v[142:145] offset:1024
	s_waitcnt vmcnt(5)
	ds_write_b128 v0, v[152:155] offset:2048
	s_waitcnt vmcnt(4)
	ds_write_b128 v0, v[156:159] offset:3072
	s_waitcnt vmcnt(3)
	ds_write_b128 v0, v[160:163] offset:4096
	s_waitcnt vmcnt(2)
	ds_write_b128 v0, v[164:167] offset:5120
	s_waitcnt vmcnt(1)
	ds_write_b128 v0, v[168:171] offset:6144
	global_load_dwordx4 v[138:141], v[176:177], off
	global_load_dwordx4 v[142:145], v[176:177], off offset:1024
	global_load_dwordx4 v[152:155], v[176:177], off offset:2048
	global_load_dwordx4 v[156:159], v[176:177], off offset:3072
	global_load_dwordx4 v[160:163], v[192:193], off offset:-4096
	global_load_dwordx4 v[164:167], v[178:179], off offset:1024
	global_load_dwordx4 v[168:171], v[178:179], off offset:2048
	s_nop 0
	global_load_dwordx4 v[176:179], v[178:179], off offset:3072
	s_nop 0
	global_load_dwordx4 v[180:183], v[192:193], off
	global_load_dwordx4 v[184:187], v[192:193], off offset:1024
	global_load_dwordx4 v[188:191], v[192:193], off offset:2048
	s_nop 0
	global_load_dwordx4 v[192:195], v[192:193], off offset:3072
	s_nop 0
	global_load_dwordx4 v[196:199], v[212:213], off offset:-4096
	global_load_dwordx4 v[200:203], v[208:209], off offset:1024
	global_load_dwordx4 v[204:207], v[208:209], off offset:2048
	s_nop 0
	global_load_dwordx4 v[208:211], v[208:209], off offset:3072
	s_nop 0
	global_load_dwordx4 v[216:219], v[212:213], off
	global_load_dwordx4 v[220:223], v[212:213], off offset:1024
	global_load_dwordx4 v[224:227], v[212:213], off offset:2048
	global_load_dwordx4 v[228:231], v[212:213], off offset:3072
	global_load_dwordx4 v[234:237], v[34:35], off
	global_load_dwordx4 v[242:245], v[34:35], off offset:1024
	global_load_dwordx4 v[246:249], v[34:35], off offset:2048
	s_nop 0
	global_load_dwordx4 v[34:37], v[34:35], off offset:3072
	s_waitcnt vmcnt(24)
	ds_write_b128 v0, v[172:175] offset:7168
	s_waitcnt vmcnt(23)
	ds_write_b128 v0, v[138:141] offset:8192
	s_waitcnt vmcnt(22)
	ds_write_b128 v0, v[142:145] offset:9216
	s_waitcnt vmcnt(21)
	ds_write_b128 v0, v[152:155] offset:10240
	s_waitcnt vmcnt(20)
	ds_write_b128 v0, v[156:159] offset:11264
	s_waitcnt vmcnt(19)
	ds_write_b128 v0, v[160:163] offset:12288
	s_waitcnt vmcnt(18)
	ds_write_b128 v0, v[164:167] offset:13312
	s_waitcnt vmcnt(17)
	ds_write_b128 v0, v[168:171] offset:14336
	s_waitcnt vmcnt(16)
	ds_write_b128 v0, v[176:179] offset:15360
	s_waitcnt vmcnt(15)
	ds_write_b128 v0, v[180:183] offset:16384
	s_waitcnt vmcnt(14)
	ds_write_b128 v0, v[184:187] offset:17408
	s_waitcnt vmcnt(13)
	ds_write_b128 v0, v[188:191] offset:18432
	s_waitcnt vmcnt(12)
; __device__ __forceinline__ unsigned cvt_pk_bf16_c(float lo, float hi) { const f32x2_t v = {lo, hi}; return __builtin_bit_cast(unsigned, __builtin_convertvector(v, bf16x2_t)); }
; #define LAS __attribute__((address_space(3)))
; __device__ __forceinline__ void store_wt(void* p, const u32x4 v) { asm volatile("global_store_dwordx4 %0, %1, off sc1\n\ts_nop 2" :: "v"(p), "v"(v) : "memory"); }
; __device__ __forceinline__ void hgrn_h2(LAS unsigned char* lds, bf16_t* DS, const float* DEC, int cid, int G, int tid) {
;     ...
;         bf16_t* p = DS + (size_t)bh * NCH * (HD * HD) + (size_t)v * HD + d; const float* dp = DEC + (size_t)bh * NCH * HD;
;         float S[8];
; #pragma unroll
;         for (int j = 0; j < 8; ++j) S[j] = 0.f;
;         u32x4 raw[32];
; #pragma unroll
;         for (int j = 0; j < 32; ++j) raw[j] = *(const u32x4*)(p + (size_t)j * (HD * HD));
;         asm volatile("s_waitcnt lgkmcnt(0)" ::: "memory");
; #pragma unroll
;         for (int h = 0; h < 4; ++h) { f32x4 t[8];
; #pragma unroll
;             for (int j = 0; j < 8; ++j) t[j] = *(const f32x4*)(dp + 4 * (lane + 64 * (8 * h + j)));
; #pragma unroll
;             for (int j = 0; j < 8; ++j) *(LAS f32x4*)(DL + 4 * (lane + 64 * (8 * h + j))) = t[j]; }
;         asm volatile("s_waitcnt lgkmcnt(0)" ::: "memory");
; #pragma unroll 1
;         for (int n0 = 0; n0 < NCH; n0 += 32) {
; #pragma unroll
;             for (int j = 0; j < 32; ++j) { u32x4 o; o.x = cvt_pk_bf16_c(S[0], S[1]); o.y = cvt_pk_bf16_c(S[2], S[3]); o.z = cvt_pk_bf16_c(S[4], S[5]); o.w = cvt_pk_bf16_c(S[6], S[7]);
;                 float t[8]; unpack8(raw[j], t);
;                 if (n0 + 32 < NCH) raw[j] = *(const u32x4*)(p + (size_t)(n0 + 32 + j) * (HD * HD));
;                 store_wt(p + (size_t)(n0 + j) * (HD * HD), o);
;                 const f32x4 dc0 = *(const LAS f32x4*)(DL + (n0 + j) * HD + d), dc1 = *(const LAS f32x4*)(DL + (n0 + j) * HD + d + 4);
	ds_write_b128 v0, v[192:195] offset:19456
	s_waitcnt vmcnt(11)
	ds_write_b128 v0, v[196:199] offset:20480
	s_waitcnt vmcnt(10)
	ds_write_b128 v0, v[200:203] offset:21504
	s_waitcnt vmcnt(9)
	ds_write_b128 v0, v[204:207] offset:22528
	s_waitcnt vmcnt(8)
	ds_write_b128 v0, v[208:211] offset:23552
	s_waitcnt vmcnt(7)
	ds_write_b128 v0, v[216:219] offset:24576
	s_waitcnt vmcnt(6)
	ds_write_b128 v0, v[220:223] offset:25600
	s_waitcnt vmcnt(5)
	ds_write_b128 v0, v[224:227] offset:26624
	s_waitcnt vmcnt(4)
	ds_write_b128 v0, v[228:231] offset:27648
	s_waitcnt vmcnt(3)
	ds_write_b128 v0, v[234:237] offset:28672
	s_waitcnt vmcnt(2)
	ds_write_b128 v0, v[242:245] offset:29696
	s_waitcnt vmcnt(1)
	ds_write_b128 v0, v[246:249] offset:30720
	s_waitcnt vmcnt(0)
	ds_write_b128 v0, v[34:37] offset:31744
	v_lshl_add_u64 v[152:153], v[150:151], 0, s[6:7]
	s_mov_b64 s[6:7], 0x108000
	v_lshl_add_u64 v[154:155], v[150:151], 0, s[6:7]
	s_mov_b64 s[6:7], 0x110000
	v_lshl_add_u64 v[156:157], v[150:151], 0, s[6:7]
	s_mov_b64 s[6:7], 0x118000
	v_lshl_add_u64 v[158:159], v[150:151], 0, s[6:7]
	s_mov_b64 s[6:7], 0x120000
	v_lshl_add_u64 v[160:161], v[150:151], 0, s[6:7]
	s_mov_b64 s[6:7], 0x128000
	v_lshl_add_u64 v[162:163], v[150:151], 0, s[6:7]
	s_mov_b64 s[6:7], 0x130000
	v_lshl_add_u64 v[164:165], v[150:151], 0, s[6:7]
	s_mov_b64 s[6:7], 0x138000
	v_lshl_add_u64 v[166:167], v[150:151], 0, s[6:7]
	s_mov_b64 s[6:7], 0x140000
	v_lshl_add_u64 v[168:169], v[150:151], 0, s[6:7]
	s_mov_b64 s[6:7], 0x148000
	v_lshl_add_u64 v[170:171], v[150:151], 0, s[6:7]
	s_mov_b64 s[6:7], 0x150000
	v_lshl_add_u64 v[172:173], v[150:151], 0, s[6:7]
	s_mov_b64 s[6:7], 0x158000
	v_lshl_add_u64 v[174:175], v[150:151], 0, s[6:7]
	s_mov_b64 s[6:7], 0x160000
	v_lshl_add_u64 v[176:177], v[150:151], 0, s[6:7]
	s_mov_b64 s[6:7], 0x168000
	v_lshl_add_u64 v[178:179], v[150:151], 0, s[6:7]
	s_mov_b64 s[6:7], 0x170000
	v_lshl_add_u64 v[180:181], v[150:151], 0, s[6:7]
	s_mov_b64 s[6:7], 0x178000
	v_lshl_add_u64 v[182:183], v[150:151], 0, s[6:7]
	s_mov_b64 s[6:7], 0x180000
	v_lshl_add_u64 v[184:185], v[150:151], 0, s[6:7]
	s_mov_b64 s[6:7], 0x188000
	v_lshl_add_u64 v[186:187], v[150:151], 0, s[6:7]
	s_mov_b64 s[6:7], 0x190000
	v_lshl_add_u64 v[188:189], v[150:151], 0, s[6:7]
	s_mov_b64 s[6:7], 0x198000
	v_lshl_add_u64 v[190:191], v[150:151], 0, s[6:7]
	s_mov_b64 s[6:7], 0x1a0000
	v_lshl_add_u64 v[192:193], v[150:151], 0, s[6:7]
	s_mov_b64 s[6:7], 0x1a8000
	v_lshl_add_u64 v[194:195], v[150:151], 0, s[6:7]
	s_mov_b64 s[6:7], 0x1b0000
	v_lshl_add_u64 v[196:197], v[150:151], 0, s[6:7]
	s_mov_b64 s[6:7], 0x1b8000
	v_lshl_add_u64 v[198:199], v[150:151], 0, s[6:7]
	s_mov_b64 s[6:7], 0x1c0000
	v_lshl_add_u64 v[200:201], v[150:151], 0, s[6:7]
	s_mov_b64 s[6:7], 0x1c8000
	v_lshl_add_u64 v[202:203], v[150:151], 0, s[6:7]
	s_mov_b64 s[6:7], 0x1d0000
	v_lshl_add_u64 v[204:205], v[150:151], 0, s[6:7]
	s_mov_b64 s[6:7], 0x1d8000
	v_lshl_add_u64 v[206:207], v[150:151], 0, s[6:7]
	s_mov_b64 s[6:7], 0x1e0000
	v_lshl_add_u64 v[208:209], v[150:151], 0, s[6:7]
	s_mov_b64 s[6:7], 0x1e8000
	s_waitcnt lgkmcnt(0)
	v_lshl_add_u64 v[210:211], v[150:151], 0, s[6:7]
	s_mov_b64 s[6:7], 0x1f0000
	v_lshl_add_u64 v[216:217], v[150:151], 0, s[6:7]
	s_mov_b64 s[6:7], 0x1f8000
	v_mov_b32_e32 v220, 0
	v_mov_b64_e32 v[34:35], v[54:55]
	v_bfe_u32 v0, v232, 6, 2
	v_lshlrev_b32_e32 v0, 7, v0
	v_and_b32_e32 v250, 3, v232
	v_lshl_add_u32 v0, v250, 5, v0
	v_add_u32_e32 v0, v0, v233
	v_lshl_add_u64 v[218:219], v[150:151], 0, s[6:7]
	v_mov_b32_e32 v221, v220
	v_mov_b32_e32 v222, v220
	v_mov_b32_e32 v223, v220
	v_mov_b32_e32 v224, v220
	v_mov_b32_e32 v225, v220
	v_mov_b32_e32 v226, v220
	v_mov_b32_e32 v227, v220
	v_mov_b64_e32 v[36:37], v[56:57]
	s_branch .LBB0_823

;     __host__ __device__ __forceinline__ int item(int k) const { const int vv = vid + (k >> 3) * G; if (vv >= 256) return -1; const int pm = vv >> 2, p = vv & 3, j = k & 7; return (((pm >> 4) * 8 + 2 * p + (j >> 2)) << 6) + (pm & 15) * 4 + (j & 3); }
; __device__ __forceinline__ void hgrn_h3(LAS unsigned char* lds, const bf16_t* Q, const _Float16* LF, const bf16_t* V, const bf16_t* SG, const bf16_t* SP, const float* gn, bf16_t* YAB, int cid, int G, int tid) {
;     ...
;     for (int p = 0; h3_item(cid, G, 0, p) < NB * NH * NCH; ++p, item = h3_item(cid, G, grp, p)) {
;         const bool act = item < NB * NH * NCH;
;         int lane = lane0; asm volatile("" : "+v"(lane));
;         const int fr = lane & 15, fq = lane >> 4, tg = wl * 64 + lane;
;         const int bh = item >> 6, n = item & 63, b_ = bh >> 3, h = bh & 7; const size_t row0 = (size_t)b_ * SEQ + (size_t)n * CH;
;         const size_t grow = row0 + 16 * tt + fr;
;         const bf16_t* spp = SP + (size_t)item * (HD * HD);
;         bf16x8 sf[3][8]; u32x4 qr[4];
;         if (act) {
; #pragma unroll
;             for (int kd = 0; kd < 2; ++kd)
; #pragma unroll
;                 for (int vt = 0; vt < 8; ++vt) sf[kd][vt] = *(const bf16x8*)(spp + (size_t)(16 * vt + fr) * HD + 32 * kd + 8 * fq);
; #pragma unroll
;             for (int kd = 0; kd < 4; ++kd) qr[kd] = *(const u32x4*)(Q + grow * DH + h * 128 + 32 * kd + 8 * fq);
.LBB0_975:
	s_cmpk_lt_i32 s6, 0x800
	s_cselect_b64 s[8:9], -1, 0
	s_ashr_i32 s10, s6, 9
	s_ashr_i32 s11, s10, 31
	s_lshl_b32 s7, s6, 6
	s_lshl_b64 s[10:11], s[10:11], 12
	s_and_b32 s7, s7, 0xfc0
	s_or_b32 s10, s10, s7
	s_ashr_i32 s7, s6, 31
	s_bfe_u32 s68, s6, 0x30006
	s_or_b64 s[10:11], s[10:11], s[20:21]
	s_lshl_b64 s[28:29], s[6:7], 15
	v_mov_b32_e32 v223, v222
	s_add_u32 s28, s40, s28
	s_addc_u32 s29, s41, s29
	v_and_b32_e32 v117, 15, v223
	v_ashrrev_i32_e32 v225, 4, v223
	v_or_b32_e32 v216, s10, v117
	v_mov_b32_e32 v217, s11
	v_lshlrev_b32_e32 v2, 3, v225
	s_cmpk_gt_i32 s6, 0x7ff
	v_add_u32_e32 v224, s37, v223
	v_lshlrev_b32_e32 v0, 6, v117
	v_lshlrev_b64 v[218:219], 11, v[216:217]
	v_ashrrev_i32_e32 v3, 31, v2
	s_cbranch_scc1 .LBB0_977
; #define LAS __attribute__((address_space(3)))
; __device__ __forceinline__ void hgrn_h3(LAS unsigned char* lds, const bf16_t* Q, const _Float16* LF, const bf16_t* V, const bf16_t* SG, const bf16_t* SP, const float* gn, bf16_t* YAB, int cid, int G, int tid) {
;     ...
;         bf16x8 sf[3][8]; u32x4 qr[4];
;         if (act) {
; #pragma unroll
;             for (int kd = 0; kd < 2; ++kd)
; #pragma unroll
;                 for (int vt = 0; vt < 8; ++vt) sf[kd][vt] = *(const bf16x8*)(spp + (size_t)(16 * vt + fr) * HD + 32 * kd + 8 * fq);
; #pragma unroll
;             for (int kd = 0; kd < 4; ++kd) qr[kd] = *(const u32x4*)(Q + grow * DH + h * 128 + 32 * kd + 8 * fq);
;         }
;         if (act) {
; #pragma unroll
;             for (int j = 0; j < 4; ++j) { const int c = tg + 256 * j; const f32x8_t ff = __builtin_convertvector(lc[j], f32x8_t); LAS float* d = BM + (c >> 4) * 132 + (c & 15) * 8;
;                 *(LAS f32x4*)d = (f32x4){ff[0], ff[1], ff[2], ff[3]}; *(LAS f32x4*)(d + 4) = (f32x4){ff[4], ff[5], ff[6], ff[7]};
;                 *(LAS u32x4*)(vl + vl_off(c >> 4, c & 15)) = vr[j]; }
	s_waitcnt vmcnt(0)
	v_lshlrev_b64 v[92:93], 1, v[2:3]
	v_lshl_add_u64 v[44:45], s[28:29], 0, v[92:93]
	v_or_b32_e32 v48, 0x1000, v0
	v_mov_b32_e32 v49, v1
	v_or_b32_e32 v52, 0x2000, v0
	v_mov_b32_e32 v53, v1
	v_or_b32_e32 v54, 0x3000, v0
	v_mov_b32_e32 v55, v1
	v_lshl_add_u64 v[36:37], v[44:45], 0, v[48:49]
	v_lshl_add_u64 v[40:41], v[44:45], 0, v[52:53]
	v_lshl_add_u64 v[50:51], v[44:45], 0, v[54:55]
	v_or_b32_e32 v60, 0x4000, v0
	v_mov_b32_e32 v61, v1
	v_or_b32_e32 v62, 0x5000, v0
	v_mov_b32_e32 v63, v1
	v_lshl_add_u64 v[94:95], s[12:13], 0, v[218:219]
	s_lshl_b32 s44, s68, 8
	global_load_dwordx4 v[36:39], v[36:37], off
	s_nop 0
	global_load_dwordx4 v[40:43], v[40:41], off
	v_lshl_add_u64 v[56:57], v[44:45], 0, v[60:61]
	global_load_dwordx4 v[72:75], v[50:51], off
	global_load_dwordx4 v[68:71], v[56:57], off
	v_lshl_add_u64 v[50:51], v[44:45], 0, v[62:63]
	v_or_b32_e32 v76, 0x6000, v0
	v_mov_b32_e32 v77, v1
	v_or_b32_e32 v78, 0x7000, v0
	v_mov_b32_e32 v79, v1
	v_mov_b32_e32 v244, 64
	v_mov_b32_e32 v245, 0
	v_lshl_add_u64 v[80:81], v[244:245], 4, v[44:45]
	v_lshl_add_u64 v[94:95], v[94:95], 0, s[44:45]
	v_lshl_add_u64 v[46:47], v[44:45], 0, v[0:1]
	v_lshl_add_u64 v[56:57], v[44:45], 0, v[76:77]
	global_load_dwordx4 v[88:91], v[50:51], off
	global_load_dwordx4 v[108:111], v[56:57], off
	v_lshl_add_u64 v[50:51], v[44:45], 0, v[78:79]
	v_lshl_add_u64 v[48:49], v[80:81], 0, v[48:49]
	v_lshl_add_u64 v[52:53], v[80:81], 0, v[52:53]
	v_lshl_add_u64 v[54:55], v[80:81], 0, v[54:55]
	v_lshl_add_u64 v[60:61], v[80:81], 0, v[60:61]
	v_lshl_add_u64 v[62:63], v[80:81], 0, v[62:63]
	v_lshl_add_u64 v[76:77], v[80:81], 0, v[76:77]
	v_lshl_add_u64 v[78:79], v[80:81], 0, v[78:79]
	v_lshl_add_u64 v[92:93], v[94:95], 0, v[92:93]
	global_load_dwordx4 v[84:87], v[46:47], off
	s_nop 0
	global_load_dwordx4 v[44:47], v[46:47], off offset:1024
	s_nop 0
	global_load_dwordx4 v[112:115], v[50:51], off
	s_nop 0
	global_load_dwordx4 v[48:51], v[48:49], off
	s_nop 0
	global_load_dwordx4 v[56:59], v[52:53], off
	s_nop 0
	global_load_dwordx4 v[52:55], v[54:55], off
	s_nop 0
	global_load_dwordx4 v[64:67], v[60:61], off
	s_nop 0
	global_load_dwordx4 v[60:63], v[62:63], off
	s_nop 0
	global_load_dwordx4 v[80:83], v[76:77], off
	s_nop 0
	global_load_dwordx4 v[76:79], v[78:79], off
	s_nop 0
	global_load_dwordx4 v[104:107], v[92:93], off
	global_load_dwordx4 v[100:103], v[92:93], off offset:64
	global_load_dwordx4 v[96:99], v[92:93], off offset:128
	s_nop 0
	global_load_dwordx4 v[92:95], v[92:93], off offset:192
	s_waitcnt vmcnt(27)
	v_cvt_f32_f16_sdwa v125, v9 dst_sel:DWORD dst_unused:UNUSED_PAD src0_sel:WORD_1
	v_cvt_f32_f16_sdwa v123, v8 dst_sel:DWORD dst_unused:UNUSED_PAD src0_sel:WORD_1
	v_cvt_f32_f16_e32 v124, v9
	v_cvt_f32_f16_e32 v122, v8
	v_cvt_f32_f16_sdwa v121, v11 dst_sel:DWORD dst_unused:UNUSED_PAD src0_sel:WORD_1
	v_cvt_f32_f16_sdwa v119, v10 dst_sel:DWORD dst_unused:UNUSED_PAD src0_sel:WORD_1
	v_cvt_f32_f16_e32 v120, v11
	v_cvt_f32_f16_e32 v118, v10
	v_lshl_add_u32 v116, v117, 5, s48
	v_ashrrev_i32_e32 v128, 4, v224
	v_mad_u64_u32 v[126:127], s[6:7], v128, s62, v[116:117]
	ds_write_b128 v126, v[122:125]
	ds_write_b128 v126, v[118:121] offset:16
	v_lshlrev_b32_e32 v119, 2, v128
	v_and_b32_e32 v119, 12, v119
	v_bfe_u32 v120, v128, 2, 2
	v_bitop3_b32 v119, v119, v117, v120 bitop3:0x36
	v_lshlrev_b32_e32 v118, 8, v128
	v_lshlrev_b32_e32 v119, 4, v119
	v_add3_u32 v118, s48, v119, v118
	s_waitcnt vmcnt(25)
	v_cvt_f32_f16_sdwa v125, v17 dst_sel:DWORD dst_unused:UNUSED_PAD src0_sel:WORD_1
	v_cvt_f32_f16_sdwa v123, v16 dst_sel:DWORD dst_unused:UNUSED_PAD src0_sel:WORD_1
	v_cvt_f32_f16_e32 v124, v17
	v_cvt_f32_f16_e32 v122, v16
	ds_write_b128 v118, v[4:7] offset:51200
	v_add_u32_e32 v126, 0x100, v224
	v_cvt_f32_f16_sdwa v121, v19 dst_sel:DWORD dst_unused:UNUSED_PAD src0_sel:WORD_1
	v_cvt_f32_f16_sdwa v119, v18 dst_sel:DWORD dst_unused:UNUSED_PAD src0_sel:WORD_1
	v_cvt_f32_f16_e32 v120, v19
	v_cvt_f32_f16_e32 v118, v18
	v_ashrrev_i32_e32 v128, 4, v126
	v_mad_u64_u32 v[126:127], s[6:7], v128, s62, v[116:117]
	ds_write_b128 v126, v[122:125]
	ds_write_b128 v126, v[118:121] offset:16
	v_lshlrev_b32_e32 v119, 2, v128
	v_and_b32_e32 v119, 12, v119
	v_bfe_u32 v120, v128, 2, 2
	v_bitop3_b32 v119, v119, v117, v120 bitop3:0x36
	v_lshlrev_b32_e32 v118, 8, v128
	v_lshlrev_b32_e32 v119, 4, v119
	v_add3_u32 v118, s48, v119, v118
	s_waitcnt vmcnt(23)
	v_cvt_f32_f16_sdwa v125, v25 dst_sel:DWORD dst_unused:UNUSED_PAD src0_sel:WORD_1
	v_cvt_f32_f16_sdwa v123, v24 dst_sel:DWORD dst_unused:UNUSED_PAD src0_sel:WORD_1
	v_cvt_f32_f16_e32 v124, v25
	v_cvt_f32_f16_e32 v122, v24
	ds_write_b128 v118, v[12:15] offset:51200
	v_add_u32_e32 v126, 0x200, v224
	v_cvt_f32_f16_sdwa v121, v27 dst_sel:DWORD dst_unused:UNUSED_PAD src0_sel:WORD_1
	v_cvt_f32_f16_sdwa v119, v26 dst_sel:DWORD dst_unused:UNUSED_PAD src0_sel:WORD_1
	v_cvt_f32_f16_e32 v120, v27
	v_cvt_f32_f16_e32 v118, v26
	v_ashrrev_i32_e32 v128, 4, v126
	v_mad_u64_u32 v[126:127], s[6:7], v128, s62, v[116:117]
	ds_write_b128 v126, v[122:125]
	ds_write_b128 v126, v[118:121] offset:16
	v_lshlrev_b32_e32 v119, 2, v128
	v_and_b32_e32 v119, 12, v119
	v_bfe_u32 v120, v128, 2, 2
	v_bitop3_b32 v119, v119, v117, v120 bitop3:0x36
	v_lshlrev_b32_e32 v118, 8, v128
	v_lshlrev_b32_e32 v119, 4, v119
	v_add3_u32 v118, s48, v119, v118
	s_waitcnt vmcnt(21)
	v_cvt_f32_f16_sdwa v125, v33 dst_sel:DWORD dst_unused:UNUSED_PAD src0_sel:WORD_1
	v_cvt_f32_f16_sdwa v123, v32 dst_sel:DWORD dst_unused:UNUSED_PAD src0_sel:WORD_1
	v_cvt_f32_f16_e32 v124, v33
	v_cvt_f32_f16_e32 v122, v32
	ds_write_b128 v118, v[20:23] offset:51200
	v_add_u32_e32 v126, 0x300, v224
	v_cvt_f32_f16_sdwa v121, v35 dst_sel:DWORD dst_unused:UNUSED_PAD src0_sel:WORD_1
	v_cvt_f32_f16_sdwa v119, v34 dst_sel:DWORD dst_unused:UNUSED_PAD src0_sel:WORD_1
	v_cvt_f32_f16_e32 v120, v35
	v_cvt_f32_f16_e32 v118, v34
	v_ashrrev_i32_e32 v128, 4, v126
	v_mad_u64_u32 v[126:127], s[6:7], v128, s62, v[116:117]
	ds_write_b128 v126, v[122:125]
	ds_write_b128 v126, v[118:121] offset:16
	v_lshlrev_b32_e32 v118, 2, v128
	v_and_b32_e32 v118, 12, v118
	v_bfe_u32 v119, v128, 2, 2
	v_bitop3_b32 v118, v118, v117, v119 bitop3:0x36
	v_lshlrev_b32_e32 v116, 8, v128
	v_lshlrev_b32_e32 v118, 4, v118
	v_add3_u32 v116, s48, v118, v116
	s_waitcnt vmcnt(20)
	ds_write_b128 v116, v[28:31] offset:51200

; #define LAS __attribute__((address_space(3)))
; __device__ __forceinline__ bf16x8 pack8f(const float (&v)[8]) { u32x4 pk; pk.x = cvt_pk_bf16_c(v[0], v[1]); pk.y = cvt_pk_bf16_c(v[2], v[3]); pk.z = cvt_pk_bf16_c(v[4], v[5]); pk.w = cvt_pk_bf16_c(v[6], v[7]); return __builtin_bit_cast(bf16x8, pk); }
; __device__ __forceinline__ void hgrn_h3(LAS unsigned char* lds, const bf16_t* Q, const _Float16* LF, const bf16_t* V, const bf16_t* SG, const bf16_t* SP, const float* gn, bf16_t* YAB, int cid, int G, int tid) {
;     ...
;         if (act) {
;             f32x4 acc[8], pt[4];
; #pragma unroll
;             for (int vt = 0; vt < 8; ++vt) sf[2][vt] = *(const bf16x8*)(spp + (size_t)(16 * vt + fr) * HD + 32 * 2 + 8 * fq);
;             const int vsw = (fq & 1) ? 16 + 4 * (fq - 1) : 4 * fq;
;             u32x4 sgw[4];
; #pragma unroll
;             for (int vt = 0; vt < 8; ++vt) acc[vt] = (f32x4){0.f, 0.f, 0.f, 0.f};
; #pragma unroll
;             for (int st = 0; st < 4; ++st) pt[st] = (f32x4){0.f, 0.f, 0.f, 0.f};
; #pragma unroll
;             for (int kd = 0; kd < 4; ++kd) {
;                 float q8[8], bt[8]; unpack8(qr[kd], q8);
;                 { const f32x4 b0 = *(const LAS f32x4*)(BM + (16 * tt + fr) * 132 + 32 * kd + 8 * fq), b1 = *(const LAS f32x4*)(BM + (16 * tt + fr) * 132 + 32 * kd + 8 * fq + 4);
;                   bt[0] = b0.x; bt[1] = b0.y; bt[2] = b0.z; bt[3] = b0.w; bt[4] = b1.x; bt[5] = b1.y; bt[6] = b1.z; bt[7] = b1.w; }
; #pragma unroll
;                 for (int st = 0; st < 4; ++st) if (st <= tt) {
;                     const f32x4 r0 = *(const LAS f32x4*)(BM + (16 * st + 15) * 132 + 32 * kd + 8 * fq), r1 = *(const LAS f32x4*)(BM + (16 * st + 15) * 132 + 32 * kd + 8 * fq + 4);
;                     float e[8]; e[0] = q8[0] * __expf(bt[0] - r0.x); e[1] = q8[1] * __expf(bt[1] - r0.y); e[2] = q8[2] * __expf(bt[2] - r0.z); e[3] = q8[3] * __expf(bt[3] - r0.w);
;                     e[4] = q8[4] * __expf(bt[4] - r1.x); e[5] = q8[5] * __expf(bt[5] - r1.y); e[6] = q8[6] * __expf(bt[6] - r1.z); e[7] = q8[7] * __expf(bt[7] - r1.w);
;                     const bf16x8 qf = pack8f(e);
;                     const bf16x8 kf = *(const LAS bf16x8*)(KB + ((16 * st + fr) * 136 + 32 * kd + 8 * fq) * 2);
;                     pt[st] = __builtin_amdgcn_mfma_f32_16x16x32_bf16(kf, qf, pt[st], 0, 0, 0); }
.LBB0_990:
	s_and_b64 vcc, exec, s[6:7]
	s_cbranch_vccnz .LBB0_1028
	v_lshl_add_u64 v[118:119], s[28:29], 0, v[0:1]
	v_lshl_add_u64 v[196:197], v[2:3], 1, v[118:119]
	v_add_co_u32_e32 v118, vcc, 0x1000, v196
	global_load_dwordx4 v[120:123], v[196:197], off offset:2048
	s_nop 0
	v_addc_co_u32_e32 v119, vcc, 0, v197, vcc
	global_load_dwordx4 v[132:135], v[118:119], off offset:2048
	v_add_co_u32_e32 v118, vcc, 0x2000, v196
	v_or_b32_e32 v217, s20, v117
	s_nop 0
	v_addc_co_u32_e32 v119, vcc, 0, v197, vcc
	global_load_dwordx4 v[136:139], v[118:119], off offset:2048
	v_add_co_u32_e32 v118, vcc, 0x3000, v196
	v_lshl_add_u32 v226, v225, 5, s48
	s_nop 0
	v_addc_co_u32_e32 v119, vcc, 0, v197, vcc
	v_add_co_u32_e32 v200, vcc, s60, v196
	global_load_dwordx4 v[140:143], v[118:119], off offset:2048
	s_nop 0
	v_addc_co_u32_e32 v201, vcc, 0, v197, vcc
	global_load_dwordx4 v[144:147], v[200:201], off offset:2048
	v_add_co_u32_e32 v118, vcc, 0x5000, v196
	v_mad_u32_u24 v227, v217, s62, v226
	s_nop 0
	v_addc_co_u32_e32 v119, vcc, 0, v197, vcc
	v_add_co_u32_e32 v198, vcc, s71, v196
	global_load_dwordx4 v[148:151], v[118:119], off offset:2048
	s_nop 0
	v_addc_co_u32_e32 v199, vcc, 0, v197, vcc
	global_load_dwordx4 v[152:155], v[198:199], off offset:2048
	v_add_co_u32_e32 v118, vcc, 0x7000, v196
	s_waitcnt vmcnt(10)
	v_lshlrev_b32_e32 v172, 16, v105
	v_addc_co_u32_e32 v119, vcc, 0, v197, vcc
	global_load_dwordx4 v[156:159], v[118:119], off offset:2048
	ds_read_b128 v[164:167], v227
	ds_read_b128 v[160:163], v227 offset:16
	ds_read_b128 v[124:127], v226 offset:7920
	ds_read_b128 v[128:131], v226 offset:7936
	v_and_b32_e32 v173, 0xffff0000, v105
	v_lshlrev_b32_e32 v170, 16, v106
	v_and_b32_e32 v171, 0xffff0000, v106
	s_waitcnt lgkmcnt(1)
	v_sub_f32_e32 v0, v164, v124
	v_mul_f32_e32 v0, 0x3fb8aa3b, v0
	v_exp_f32_e32 v118, v0
	v_sub_f32_e32 v0, v165, v125
	v_mul_f32_e32 v0, 0x3fb8aa3b, v0
	v_exp_f32_e32 v119, v0
	v_sub_f32_e32 v0, v166, v126
	v_mul_f32_e32 v0, 0x3fb8aa3b, v0
	v_exp_f32_e32 v124, v0
	v_sub_f32_e32 v0, v167, v127
	v_mul_f32_e32 v0, 0x3fb8aa3b, v0
	v_exp_f32_e32 v125, v0
	s_waitcnt lgkmcnt(0)
	v_sub_f32_e32 v0, v160, v128
	v_mul_f32_e32 v0, 0x3fb8aa3b, v0
	v_lshlrev_b32_e32 v174, 16, v104
	v_pk_mul_f32 v[126:127], v[124:125], v[172:173]
	v_exp_f32_e32 v124, v0
	v_sub_f32_e32 v0, v161, v129
	v_mul_f32_e32 v0, 0x3fb8aa3b, v0
	v_exp_f32_e32 v125, v0
	v_sub_f32_e32 v0, v162, v130
	v_mul_f32_e32 v0, 0x3fb8aa3b, v0
	v_and_b32_e32 v175, 0xffff0000, v104
	v_pk_mul_f32 v[128:129], v[124:125], v[170:171]
	v_exp_f32_e32 v124, v0
	v_sub_f32_e32 v0, v163, v131
	v_mul_f32_e32 v0, 0x3fb8aa3b, v0
	v_exp_f32_e32 v125, v0
	v_lshlrev_b32_e32 v168, 16, v107
	v_and_b32_e32 v169, 0xffff0000, v107
	v_mad_u32_u24 v228, v117, s85, v2
	v_pk_mul_f32 v[118:119], v[118:119], v[174:175]
	v_pk_mul_f32 v[130:131], v[124:125], v[168:169]
	v_cvt_pk_bf16_f32 v125, v126, v127
	v_cvt_pk_bf16_f32 v126, v128, v129
	v_lshl_add_u32 v128, v228, 1, s48
	v_cvt_pk_bf16_f32 v124, v118, v119
	ds_read_b128 v[116:119], v128 offset:33792
	v_cvt_pk_bf16_f32 v127, v130, v131
	s_and_b64 vcc, exec, s[22:23]
	s_waitcnt lgkmcnt(0)
	v_mfma_f32_16x16x32_bf16 v[192:195], v[116:119], v[124:127], 0
	s_cbranch_vccz .LBB0_995
	ds_read_b128 v[116:119], v226 offset:16368
	ds_read_b128 v[124:127], v226 offset:16384
	s_waitcnt lgkmcnt(1)
	v_sub_f32_e32 v0, v164, v116
	v_mul_f32_e32 v0, 0x3fb8aa3b, v0
	v_exp_f32_e32 v2, v0
	v_sub_f32_e32 v0, v165, v117
	v_mul_f32_e32 v0, 0x3fb8aa3b, v0
	v_exp_f32_e32 v3, v0
	v_sub_f32_e32 v0, v166, v118
	v_mul_f32_e32 v0, 0x3fb8aa3b, v0
	v_exp_f32_e32 v116, v0
	v_sub_f32_e32 v0, v167, v119
	v_mul_f32_e32 v0, 0x3fb8aa3b, v0
	v_exp_f32_e32 v117, v0
	s_waitcnt lgkmcnt(0)
	v_sub_f32_e32 v0, v160, v124
	v_mul_f32_e32 v0, 0x3fb8aa3b, v0
	v_pk_mul_f32 v[2:3], v[2:3], v[174:175]
	v_pk_mul_f32 v[118:119], v[116:117], v[172:173]
	v_exp_f32_e32 v116, v0
	v_sub_f32_e32 v0, v161, v125
	v_mul_f32_e32 v0, 0x3fb8aa3b, v0
	v_exp_f32_e32 v117, v0
	v_sub_f32_e32 v0, v162, v126
	v_mul_f32_e32 v0, 0x3fb8aa3b, v0
	v_pk_mul_f32 v[124:125], v[116:117], v[170:171]
	v_exp_f32_e32 v116, v0
	v_sub_f32_e32 v0, v163, v127
	v_mul_f32_e32 v0, 0x3fb8aa3b, v0
	v_exp_f32_e32 v117, v0
	s_nop 0
	v_pk_mul_f32 v[126:127], v[116:117], v[168:169]
	v_cvt_pk_bf16_f32 v117, v118, v119
	v_cvt_pk_bf16_f32 v118, v124, v125
	v_cvt_pk_bf16_f32 v119, v126, v127
	ds_read_b128 v[124:127], v128 offset:38144
	v_cvt_pk_bf16_f32 v116, v2, v3
	s_waitcnt lgkmcnt(0)
	s_nop 0
	v_mfma_f32_16x16x32_bf16 v[124:127], v[124:127], v[116:119], 0
	v_cndmask_b32_e64 v0, 0, 1, s[24:25]
	v_cmp_ne_u32_e64 s[6:7], 1, v0
	s_andn2_b64 vcc, exec, s[24:25]
	s_cbranch_vccnz .LBB0_996

; #define LAS __attribute__((address_space(3)))
; __device__ __forceinline__ bf16x8 pack8f(const float (&v)[8]) { u32x4 pk; pk.x = cvt_pk_bf16_c(v[0], v[1]); pk.y = cvt_pk_bf16_c(v[2], v[3]); pk.z = cvt_pk_bf16_c(v[4], v[5]); pk.w = cvt_pk_bf16_c(v[6], v[7]); return __builtin_bit_cast(bf16x8, pk); }
; __device__ __forceinline__ void hgrn_h3(LAS unsigned char* lds, const bf16_t* Q, const _Float16* LF, const bf16_t* V, const bf16_t* SG, const bf16_t* SP, const float* gn, bf16_t* YAB, int cid, int G, int tid) {
;     ...
;             for (int kd = 0; kd < 4; ++kd) {
;                 float q8[8], bt[8]; unpack8(qr[kd], q8);
;                 { const f32x4 b0 = *(const LAS f32x4*)(BM + (16 * tt + fr) * 132 + 32 * kd + 8 * fq), b1 = *(const LAS f32x4*)(BM + (16 * tt + fr) * 132 + 32 * kd + 8 * fq + 4);
;                   bt[0] = b0.x; bt[1] = b0.y; bt[2] = b0.z; bt[3] = b0.w; bt[4] = b1.x; bt[5] = b1.y; bt[6] = b1.z; bt[7] = b1.w; }
; #pragma unroll
;                 for (int st = 0; st < 4; ++st) if (st <= tt) {
;                     const f32x4 r0 = *(const LAS f32x4*)(BM + (16 * st + 15) * 132 + 32 * kd + 8 * fq), r1 = *(const LAS f32x4*)(BM + (16 * st + 15) * 132 + 32 * kd + 8 * fq + 4);
;                     float e[8]; e[0] = q8[0] * __expf(bt[0] - r0.x); e[1] = q8[1] * __expf(bt[1] - r0.y); e[2] = q8[2] * __expf(bt[2] - r0.z); e[3] = q8[3] * __expf(bt[3] - r0.w);
;                     e[4] = q8[4] * __expf(bt[4] - r1.x); e[5] = q8[5] * __expf(bt[5] - r1.y); e[6] = q8[6] * __expf(bt[6] - r1.z); e[7] = q8[7] * __expf(bt[7] - r1.w);
;                     const bf16x8 qf = pack8f(e);
;                     const bf16x8 kf = *(const LAS bf16x8*)(KB + ((16 * st + fr) * 136 + 32 * kd + 8 * fq) * 2);
;                     pt[st] = __builtin_amdgcn_mfma_f32_16x16x32_bf16(kf, qf, pt[st], 0, 0, 0); }
;                 { float e[8];
; #pragma unroll
;                   for (int j = 0; j < 8; ++j) e[j] = q8[j] * __expf(bt[j]);
;                   const bf16x8 qb = pack8f(e);
; #pragma unroll
;                   for (int vt = 0; vt < 8; ++vt) acc[vt] = __builtin_amdgcn_mfma_f32_16x16x32_bf16(sf[kd % 3][vt], qb, acc[vt], 0, 0, 0); }
;                 if (kd == 0) {
; #pragma unroll
;                     for (int vt = 0; vt < 8; ++vt) sf[0][vt] = *(const bf16x8*)(spp + (size_t)(16 * vt + fr) * HD + 32 * 3 + 8 * fq); }
.LBB0_998:
	v_mul_f32_e32 v0, 0x3fb8aa3b, v164
	v_exp_f32_e32 v2, v0
	v_mul_f32_e32 v0, 0x3fb8aa3b, v165
	v_exp_f32_e32 v3, v0
	v_mul_f32_e32 v0, 0x3fb8aa3b, v166
	v_exp_f32_e32 v164, v0
	v_mul_f32_e32 v0, 0x3fb8aa3b, v167
	v_exp_f32_e32 v165, v0
	v_mul_f32_e32 v0, 0x3fb8aa3b, v160
	v_exp_f32_e32 v160, v0
	v_mul_f32_e32 v0, 0x3fb8aa3b, v161
	v_exp_f32_e32 v161, v0
	v_mul_f32_e32 v0, 0x3fb8aa3b, v162
	v_exp_f32_e32 v162, v0
	v_mul_f32_e32 v0, 0x3fb8aa3b, v163
	v_exp_f32_e32 v163, v0
	v_pk_mul_f32 v[2:3], v[2:3], v[174:175]
	s_movk_i32 s10, 0x1000
	v_pk_mul_f32 v[164:165], v[164:165], v[172:173]
	v_pk_mul_f32 v[160:161], v[160:161], v[170:171]
	v_pk_mul_f32 v[162:163], v[162:163], v[168:169]
	v_cvt_pk_bf16_f32 v188, v2, v3
	v_add_co_u32_e32 v2, vcc, s10, v196
	v_cvt_pk_bf16_f32 v189, v164, v165
	v_cvt_pk_bf16_f32 v190, v160, v161
	v_cvt_pk_bf16_f32 v191, v162, v163
	v_addc_co_u32_e32 v3, vcc, 0, v197, vcc
	s_nop 0
	v_mfma_f32_16x16x32_bf16 v[160:163], v[84:87], v[188:191], 0
	global_load_dwordx4 v[84:87], v[196:197], off offset:3072
	s_waitcnt vmcnt(11)
	v_lshlrev_b32_e32 v208, 16, v100
	v_and_b32_e32 v209, 0xffff0000, v100
	v_mfma_f32_16x16x32_bf16 v[164:167], v[36:39], v[188:191], 0
	global_load_dwordx4 v[36:39], v[2:3], off offset:3072
	v_add_co_u32_e32 v2, vcc, s65, v196
	v_mfma_f32_16x16x32_bf16 v[168:171], v[40:43], v[188:191], 0
	s_nop 0
	v_addc_co_u32_e32 v3, vcc, 0, v197, vcc
	global_load_dwordx4 v[40:43], v[2:3], off offset:3072
	v_add_co_u32_e32 v2, vcc, s80, v196
	v_mfma_f32_16x16x32_bf16 v[172:175], v[72:75], v[188:191], 0
	s_nop 0
	v_addc_co_u32_e32 v3, vcc, 0, v197, vcc
	v_lshlrev_b32_e32 v206, 16, v101
	v_mfma_f32_16x16x32_bf16 v[176:179], v[68:71], v[188:191], 0
	global_load_dwordx4 v[72:75], v[2:3], off offset:3072
	global_load_dwordx4 v[68:71], v[200:201], off offset:3072
	v_add_co_u32_e32 v2, vcc, s82, v196
	v_mfma_f32_16x16x32_bf16 v[180:183], v[88:91], v[188:191], 0
	s_nop 0
	v_addc_co_u32_e32 v3, vcc, 0, v197, vcc
	v_and_b32_e32 v207, 0xffff0000, v101
	v_mfma_f32_16x16x32_bf16 v[184:187], v[108:111], v[188:191], 0
	global_load_dwordx4 v[88:91], v[2:3], off offset:3072
	global_load_dwordx4 v[108:111], v[198:199], off offset:3072
	v_add_co_u32_e32 v2, vcc, s81, v196
	v_mfma_f32_16x16x32_bf16 v[188:191], v[112:115], v[188:191], 0
	s_nop 0
	v_addc_co_u32_e32 v3, vcc, 0, v197, vcc
	global_load_dwordx4 v[112:115], v[2:3], off offset:3072
	ds_read_b128 v[200:203], v227 offset:128
	ds_read_b128 v[196:199], v227 offset:144
	ds_read_b128 v[230:233], v226 offset:8048
	ds_read_b128 v[234:237], v226 offset:8064
	v_lshlrev_b32_e32 v204, 16, v102
	v_and_b32_e32 v205, 0xffff0000, v102
	v_lshlrev_b32_e32 v2, 16, v103
	s_waitcnt lgkmcnt(1)
	v_sub_f32_e32 v0, v200, v230
	v_mul_f32_e32 v0, 0x3fb8aa3b, v0
	v_exp_f32_e32 v210, v0
	v_sub_f32_e32 v0, v201, v231
	v_mul_f32_e32 v0, 0x3fb8aa3b, v0
	v_exp_f32_e32 v211, v0
	v_sub_f32_e32 v0, v202, v232
	v_mul_f32_e32 v0, 0x3fb8aa3b, v0
	v_exp_f32_e32 v212, v0
	v_sub_f32_e32 v0, v203, v233
	v_mul_f32_e32 v0, 0x3fb8aa3b, v0
	v_exp_f32_e32 v213, v0
	s_waitcnt lgkmcnt(0)
	v_sub_f32_e32 v0, v196, v234
	v_mul_f32_e32 v0, 0x3fb8aa3b, v0
	v_exp_f32_e32 v214, v0
	v_sub_f32_e32 v0, v197, v235
	v_mul_f32_e32 v0, 0x3fb8aa3b, v0
	v_exp_f32_e32 v215, v0
	v_sub_f32_e32 v0, v198, v236
	v_mul_f32_e32 v0, 0x3fb8aa3b, v0
	v_exp_f32_e32 v220, v0
	v_sub_f32_e32 v0, v199, v237
	v_mul_f32_e32 v0, 0x3fb8aa3b, v0
	v_exp_f32_e32 v221, v0
	v_add_u32_e32 v0, 32, v228
	v_lshl_add_u32 v0, v0, 1, s48
	ds_read_b128 v[234:237], v0 offset:33792
	v_and_b32_e32 v3, 0xffff0000, v103
	v_pk_mul_f32 v[210:211], v[210:211], v[208:209]
	v_pk_mul_f32 v[212:213], v[212:213], v[206:207]
	v_pk_mul_f32 v[214:215], v[214:215], v[204:205]
	v_pk_mul_f32 v[220:221], v[220:221], v[2:3]
	v_cvt_pk_bf16_f32 v230, v210, v211
	v_cvt_pk_bf16_f32 v231, v212, v213
	v_cvt_pk_bf16_f32 v232, v214, v215
	v_cvt_pk_bf16_f32 v233, v220, v221
	v_cndmask_b32_e64 v210, 0, 1, s[22:23]
	v_cmp_ne_u32_e64 s[10:11], 1, v210
	s_waitcnt lgkmcnt(0)
	v_mfma_f32_16x16x32_bf16 v[192:195], v[234:237], v[230:233], v[192:195]
	s_andn2_b64 vcc, exec, s[22:23]
	s_cbranch_vccnz .LBB0_1000
	ds_read_b128 v[230:233], v226 offset:16496
	ds_read_b128 v[234:237], v226 offset:16512
	s_waitcnt lgkmcnt(1)
	v_sub_f32_e32 v210, v200, v230
	s_waitcnt lgkmcnt(0)
	v_sub_f32_e32 v214, v196, v234
	v_sub_f32_e32 v215, v197, v235
	v_sub_f32_e32 v220, v198, v236
	v_sub_f32_e32 v221, v199, v237
	ds_read_b128 v[234:237], v0 offset:38144
	v_sub_f32_e32 v211, v201, v231
	v_sub_f32_e32 v212, v202, v232
	v_sub_f32_e32 v213, v203, v233
	v_mul_f32_e32 v210, 0x3fb8aa3b, v210
	v_mul_f32_e32 v211, 0x3fb8aa3b, v211
	v_mul_f32_e32 v212, 0x3fb8aa3b, v212
	v_mul_f32_e32 v213, 0x3fb8aa3b, v213
	v_mul_f32_e32 v214, 0x3fb8aa3b, v214
	v_mul_f32_e32 v215, 0x3fb8aa3b, v215
	v_mul_f32_e32 v220, 0x3fb8aa3b, v220
	v_mul_f32_e32 v221, 0x3fb8aa3b, v221
	v_exp_f32_e32 v210, v210
	v_exp_f32_e32 v211, v211
	v_exp_f32_e32 v212, v212
	v_exp_f32_e32 v213, v213
	v_exp_f32_e32 v214, v214
	v_exp_f32_e32 v215, v215
	v_exp_f32_e32 v220, v220
	v_exp_f32_e32 v221, v221
	v_pk_mul_f32 v[210:211], v[210:211], v[208:209]
	v_pk_mul_f32 v[212:213], v[212:213], v[206:207]
	v_pk_mul_f32 v[214:215], v[214:215], v[204:205]
	v_pk_mul_f32 v[220:221], v[220:221], v[2:3]
	v_cvt_pk_bf16_f32 v230, v210, v211
	v_cvt_pk_bf16_f32 v231, v212, v213
	v_cvt_pk_bf16_f32 v232, v214, v215
	v_cvt_pk_bf16_f32 v233, v220, v221
	s_waitcnt lgkmcnt(0)
	s_nop 0
	v_mfma_f32_16x16x32_bf16 v[124:127], v[234:237], v[230:233], v[124:127]
